# fast back edge with one compare and one branch; in-loop pointer select without the mask round trip
# baseline (speedup 1.0000x reference)
; #define G_STAGE(bufoff, gbase) do { _Pragma("unroll") for (int _i = 0; _i < 2; ++_i) \
;         __builtin_amdgcn_global_load_lds((const unsigned*)((const char*)(gbase) + voff[_i]), (LAS unsigned*)(lds + (bufoff) + ldsw + _i * 8192), 16, 0, 0); } while (0)
; #define G_LDA(dst, b, h) do { _Pragma("unroll") for (int m = 0; m < 4; ++m) _Pragma("unroll") for (int k = 0; k < 2; ++k) dst[m][k] = *(const LAS bf16x8*)(lds + G_SA(b, h) + aoff + m * 2048 + k * 1024); } while (0)
; #define G_LDB(dst, b, h) do { _Pragma("unroll") for (int n = 0; n < 2; ++n) _Pragma("unroll") for (int k = 0; k < 2; ++k) dst[n][k] = *(const LAS bf16x8*)(lds + G_SB(b, h) + boff + n * 2048 + k * 1024); } while (0)
; #define G_MMA(ai, bj, At, Bt) do { __builtin_amdgcn_s_setprio(1); _Pragma("unroll") for (int m = 0; m < 4; ++m) _Pragma("unroll") for (int n = 0; n < 2; ++n) _Pragma("unroll") for (int k = 0; k < 2; ++k) \
;         acc[ai][bj][m][n] = MFMA16(Bt[n][k], At[m][k], acc[ai][bj][m][n]); __builtin_amdgcn_s_setprio(0); } while (0)
; #define G_WAIT_V(n) asm volatile("s_waitcnt vmcnt(" #n ")" ::: "memory")
; #define G_WAIT_L(n) asm volatile("s_waitcnt lgkmcnt(" #n ")" ::: "memory")
; #define G_BAR __builtin_amdgcn_s_barrier()
; #define G_SCHED __builtin_amdgcn_sched_barrier(0)
; template <class Epi>
; __device__ __forceinline__ void gemm_phase(LAS unsigned char* lds, const bf16_t* Ag, const bf16_t* Btg, const int K, const int nM, const int nN, const Epi& E) {
;     ...
;             G_LDB(B0, 0, 0); G_SCHED; G_LDA(At, 0, 0); G_STAGE(G_SA(1, 1), a1 + hstep);
;             G_WAIT_L(8); G_BAR; G_WAIT_L(0); G_MMA(0, 0, At, B0); G_BAR; G_SCHED;
;             G_LDB(B1, 0, 1); G_STAGE(G_SB(0, 0), b2);
;             G_BAR; G_WAIT_L(0); G_MMA(0, 1, At, B1); G_BAR;
;             G_LDA(At, 0, 1); G_STAGE(G_SA(0, 0), a2);
;             G_BAR; G_WAIT_L(0); G_MMA(1, 0, At, B0); G_BAR; G_SCHED;
;             G_STAGE(G_SB(0, 1), b2 + hstep);
;             G_WAIT_V(6); G_BAR; G_MMA(1, 1, At, B1); G_BAR;
.LmainW_78:
	ds_read_b128 v[124:127], v217
	ds_read_b128 v[128:131], v217 offset:1024
	ds_read_b128 v[132:135], v217 offset:2048
	ds_read_b128 v[136:139], v217 offset:3072
	s_add_i32 m0, s58, 0xc000
	ds_read_b128 v[140:143], v186
	ds_read_b128 v[148:151], v186 offset:1024
	ds_read_b128 v[152:155], v186 offset:2048
	ds_read_b128 v[156:159], v186 offset:3072
	ds_read_b128 v[188:191], v186 offset:4096
	ds_read_b128 v[192:195], v186 offset:5120
	ds_read_b128 v[222:225], v186 offset:6144
	global_load_lds_dwordx4 v170, s[50:51]
	s_add_i32 m0, s58, 0xe000
	ds_read_b128 v[226:229], v186 offset:7168
	global_load_lds_dwordx4 v168, s[50:51]
	s_waitcnt lgkmcnt(8)
	s_barrier
	s_waitcnt lgkmcnt(0)
	v_mfma_f32_16x16x32_bf16 v[164:167], v[124:127], v[140:143], v[164:167]
	v_mfma_f32_16x16x32_bf16 v[160:163], v[132:135], v[140:143], v[160:163]
	v_mfma_f32_16x16x32_bf16 v[116:119], v[124:127], v[152:155], v[116:119]
	v_mfma_f32_16x16x32_bf16 v[112:115], v[132:135], v[152:155], v[112:115]
	v_mfma_f32_16x16x32_bf16 v[100:103], v[124:127], v[188:191], v[100:103]
	v_mfma_f32_16x16x32_bf16 v[96:99], v[132:135], v[188:191], v[96:99]
	v_mfma_f32_16x16x32_bf16 v[84:87], v[124:127], v[222:225], v[84:87]
	v_mfma_f32_16x16x32_bf16 v[80:83], v[132:135], v[222:225], v[80:83]
	v_mfma_f32_16x16x32_bf16 v[164:167], v[128:131], v[148:151], v[164:167]
	v_mfma_f32_16x16x32_bf16 v[160:163], v[136:139], v[148:151], v[160:163]
	v_mfma_f32_16x16x32_bf16 v[116:119], v[128:131], v[156:159], v[116:119]
	v_mfma_f32_16x16x32_bf16 v[112:115], v[136:139], v[156:159], v[112:115]
	v_mfma_f32_16x16x32_bf16 v[100:103], v[128:131], v[192:195], v[100:103]
	v_mfma_f32_16x16x32_bf16 v[96:99], v[136:139], v[192:195], v[96:99]
	v_mfma_f32_16x16x32_bf16 v[84:87], v[128:131], v[226:229], v[84:87]
	v_mfma_f32_16x16x32_bf16 v[80:83], v[136:139], v[226:229], v[80:83]
	s_barrier
	ds_read_b128 v[230:233], v217 offset:16384
	ds_read_b128 v[234:237], v217 offset:17408
	s_add_i32 m0, s57, 0x10000
	ds_read_b128 v[238:241], v217 offset:18432
	global_load_lds_dwordx4 v0, s[52:53]
	s_add_i32 m0, s57, 0x12000
	ds_read_b128 v[242:245], v217 offset:19456
	global_load_lds_dwordx4 v2, s[52:53]
	s_barrier
	s_waitcnt lgkmcnt(0)
	v_mfma_f32_16x16x32_bf16 v[144:147], v[230:233], v[140:143], v[144:147]
	v_mfma_f32_16x16x32_bf16 v[120:123], v[238:241], v[140:143], v[120:123]
	v_mfma_f32_16x16x32_bf16 v[108:111], v[230:233], v[152:155], v[108:111]
	v_mfma_f32_16x16x32_bf16 v[104:107], v[238:241], v[152:155], v[104:107]
	v_mfma_f32_16x16x32_bf16 v[92:95], v[230:233], v[188:191], v[92:95]
	v_mfma_f32_16x16x32_bf16 v[88:91], v[238:241], v[188:191], v[88:91]
	v_mfma_f32_16x16x32_bf16 v[76:79], v[230:233], v[222:225], v[76:79]
	v_mfma_f32_16x16x32_bf16 v[72:75], v[238:241], v[222:225], v[72:75]
	v_mfma_f32_16x16x32_bf16 v[144:147], v[234:237], v[148:151], v[144:147]
	v_mfma_f32_16x16x32_bf16 v[120:123], v[242:245], v[148:151], v[120:123]
	v_mfma_f32_16x16x32_bf16 v[108:111], v[234:237], v[156:159], v[108:111]
	v_mfma_f32_16x16x32_bf16 v[104:107], v[242:245], v[156:159], v[104:107]
	v_mfma_f32_16x16x32_bf16 v[92:95], v[234:237], v[192:195], v[92:95]
	v_mfma_f32_16x16x32_bf16 v[88:91], v[242:245], v[192:195], v[88:91]
	v_mfma_f32_16x16x32_bf16 v[76:79], v[234:237], v[226:229], v[76:79]
	v_mfma_f32_16x16x32_bf16 v[72:75], v[242:245], v[226:229], v[72:75]
	s_mov_b32 m0, s58
	s_barrier
	ds_read_b128 v[140:143], v186 offset:16384
	ds_read_b128 v[148:151], v186 offset:17408
	ds_read_b128 v[152:155], v186 offset:18432
	ds_read_b128 v[156:159], v186 offset:19456
	ds_read_b128 v[188:191], v186 offset:20480
	ds_read_b128 v[192:195], v186 offset:21504
	ds_read_b128 v[222:225], v186 offset:22528
	global_load_lds_dwordx4 v0, s[54:55]
	s_mov_b32 m0, s59
	ds_read_b128 v[226:229], v186 offset:23552
	global_load_lds_dwordx4 v2, s[54:55]
	s_barrier
	s_waitcnt lgkmcnt(0)
	v_mfma_f32_16x16x32_bf16 v[60:63], v[124:127], v[140:143], v[60:63]
	v_mfma_f32_16x16x32_bf16 v[56:59], v[132:135], v[140:143], v[56:59]
	v_mfma_f32_16x16x32_bf16 v[44:47], v[124:127], v[152:155], v[44:47]
	v_mfma_f32_16x16x32_bf16 v[40:43], v[132:135], v[152:155], v[40:43]
	v_mfma_f32_16x16x32_bf16 v[28:31], v[124:127], v[188:191], v[28:31]
	v_mfma_f32_16x16x32_bf16 v[24:27], v[132:135], v[188:191], v[24:27]
	v_mfma_f32_16x16x32_bf16 v[12:15], v[124:127], v[222:225], v[12:15]
	v_mfma_f32_16x16x32_bf16 v[8:11], v[132:135], v[222:225], v[8:11]
	v_mfma_f32_16x16x32_bf16 v[60:63], v[128:131], v[148:151], v[60:63]
	v_mfma_f32_16x16x32_bf16 v[56:59], v[136:139], v[148:151], v[56:59]
	v_mfma_f32_16x16x32_bf16 v[44:47], v[128:131], v[156:159], v[44:47]
	v_mfma_f32_16x16x32_bf16 v[40:43], v[136:139], v[156:159], v[40:43]
	v_mfma_f32_16x16x32_bf16 v[28:31], v[128:131], v[192:195], v[28:31]
	v_mfma_f32_16x16x32_bf16 v[24:27], v[136:139], v[192:195], v[24:27]
	v_mfma_f32_16x16x32_bf16 v[12:15], v[128:131], v[226:229], v[12:15]
	v_mfma_f32_16x16x32_bf16 v[8:11], v[136:139], v[226:229], v[8:11]
	s_barrier
	s_add_i32 m0, s57, 0x14000
	s_add_u32 s74, s52, 0x40000
	s_addc_u32 s75, s53, 0
	global_load_lds_dwordx4 v0, s[74:75]
	s_add_i32 m0, s57, 0x16000
	s_add_u32 s54, s54, 0x40000
	s_addc_u32 s55, s55, 0
	global_load_lds_dwordx4 v2, s[74:75]
	s_waitcnt vmcnt(6)
	s_barrier
;     __device__ __forceinline__ void prep(int pm, int par, LAS unsigned char* lds) const { if (fold) prep_rowstats(stat, pm, par, lds); }
;     __device__ __forceinline__ void prep(int pm, int par, LAS unsigned char* lds) const { if (!ident) prep_rowstats(stat, pm, par, lds); }
;     __device__ __forceinline__ void prep(int pm, int par, LAS unsigned char* lds) const { prep_rowstats(stat, pm, par, lds); }
; #define G_STAGE(bufoff, gbase) do { _Pragma("unroll") for (int _i = 0; _i < 2; ++_i) \
;         __builtin_amdgcn_global_load_lds((const unsigned*)((const char*)(gbase) + voff[_i]), (LAS unsigned*)(lds + (bufoff) + ldsw + _i * 8192), 16, 0, 0); } while (0)
; #define G_WAIT_V(n) asm volatile("s_waitcnt vmcnt(" #n ")" ::: "memory")
; #define G_BAR __builtin_amdgcn_s_barrier()
; template <class Epi>
; __device__ __forceinline__ void gemm_phase(LAS unsigned char* lds, const bf16_t* Ag, const bf16_t* Btg, const int K, const int nM, const int nN, const Epi& E) {
;     ...
;         for (int t = 0; t < nt; t += 2) {
;             const bool last = (t == nt - 2);
;             const char* a1 = cA + (size_t)(t + 1) * kstep;
;             const char* a2 = last ? nA : cA + (size_t)(t + 2) * kstep; const char* b2 = last ? nB : cB + (size_t)(t + 2) * kstep;
;             const char* a3 = a2 + kstep; const char* b3 = b2 + kstep;
;             if (last && has_next && pmn != pm) E.prep(pmn, par ^ 1, lds);
;             G_LDB(B0, 0, 0); G_SCHED; G_LDA(At, 0, 0); G_STAGE(G_SA(1, 1), a1 + hstep);
;             G_WAIT_L(8); G_BAR; G_WAIT_L(0); G_MMA(0, 0, At, B0); G_BAR; G_SCHED;
;             G_LDB(B1, 0, 1); G_STAGE(G_SB(0, 0), b2);
;             G_BAR; G_WAIT_L(0); G_MMA(0, 1, At, B1); G_BAR;
;             G_LDA(At, 0, 1); G_STAGE(G_SA(0, 0), a2);
;             G_BAR; G_WAIT_L(0); G_MMA(1, 0, At, B0); G_BAR; G_SCHED;
;             G_STAGE(G_SB(0, 1), b2 + hstep);
;             G_WAIT_V(6); G_BAR; G_MMA(1, 1, At, B1); G_BAR;
;             G_LDB(B0, 1, 0); G_SCHED; G_LDA(At, 1, 0); G_STAGE(G_SA(0, 1), a2 + hstep);
;             G_WAIT_L(8); G_BAR; G_WAIT_L(0); G_MMA(0, 0, At, B0); G_BAR; G_SCHED;
;             G_LDB(B1, 1, 1); G_STAGE(G_SB(1, 0), b3);
;             G_BAR; G_WAIT_L(0); G_MMA(0, 1, At, B1); G_BAR;
;             G_LDA(At, 1, 1); G_STAGE(G_SA(1, 0), a3);
;             G_BAR; G_WAIT_L(0); G_MMA(1, 0, At, B0); G_BAR; G_SCHED;
;             G_STAGE(G_SB(1, 1), b3 + hstep);
	v_mfma_f32_16x16x32_bf16 v[68:71], v[230:233], v[140:143], v[68:71]
	v_mfma_f32_16x16x32_bf16 v[64:67], v[238:241], v[140:143], v[64:67]
	v_mfma_f32_16x16x32_bf16 v[52:55], v[230:233], v[152:155], v[52:55]
	v_mfma_f32_16x16x32_bf16 v[48:51], v[238:241], v[152:155], v[48:51]
	v_mfma_f32_16x16x32_bf16 v[36:39], v[230:233], v[188:191], v[36:39]
	v_mfma_f32_16x16x32_bf16 v[32:35], v[238:241], v[188:191], v[32:35]
	v_mfma_f32_16x16x32_bf16 v[20:23], v[230:233], v[222:225], v[20:23]
	v_mfma_f32_16x16x32_bf16 v[16:19], v[238:241], v[222:225], v[16:19]
	v_mfma_f32_16x16x32_bf16 v[68:71], v[234:237], v[148:151], v[68:71]
	v_mfma_f32_16x16x32_bf16 v[64:67], v[242:245], v[148:151], v[64:67]
	v_mfma_f32_16x16x32_bf16 v[52:55], v[234:237], v[156:159], v[52:55]
	v_mfma_f32_16x16x32_bf16 v[48:51], v[242:245], v[156:159], v[48:51]
	v_mfma_f32_16x16x32_bf16 v[36:39], v[234:237], v[192:195], v[36:39]
	v_mfma_f32_16x16x32_bf16 v[32:35], v[242:245], v[192:195], v[32:35]
	v_mfma_f32_16x16x32_bf16 v[20:23], v[234:237], v[226:229], v[20:23]
	v_mfma_f32_16x16x32_bf16 v[16:19], v[242:245], v[226:229], v[16:19]
	s_barrier
	ds_read_b128 v[124:127], v217 offset:32768
	ds_read_b128 v[128:131], v217 offset:33792
	ds_read_b128 v[132:135], v217 offset:34816
	ds_read_b128 v[136:139], v217 offset:35840
	s_mov_b32 m0, s60
	ds_read_b128 v[140:143], v186 offset:32768
	ds_read_b128 v[148:151], v186 offset:33792
	ds_read_b128 v[152:155], v186 offset:34816
	ds_read_b128 v[156:159], v186 offset:35840
	ds_read_b128 v[188:191], v186 offset:36864
	ds_read_b128 v[192:195], v186 offset:37888
	ds_read_b128 v[222:225], v186 offset:38912
	global_load_lds_dwordx4 v0, s[54:55]
	s_mov_b32 m0, s61
	ds_read_b128 v[226:229], v186 offset:39936
	global_load_lds_dwordx4 v2, s[54:55]
	s_waitcnt lgkmcnt(8)
	s_barrier
	s_waitcnt lgkmcnt(0)
	v_mfma_f32_16x16x32_bf16 v[164:167], v[124:127], v[140:143], v[164:167]
	v_mfma_f32_16x16x32_bf16 v[160:163], v[132:135], v[140:143], v[160:163]
	v_mfma_f32_16x16x32_bf16 v[116:119], v[124:127], v[152:155], v[116:119]
	v_mfma_f32_16x16x32_bf16 v[112:115], v[132:135], v[152:155], v[112:115]
	v_mfma_f32_16x16x32_bf16 v[100:103], v[124:127], v[188:191], v[100:103]
	v_mfma_f32_16x16x32_bf16 v[96:99], v[132:135], v[188:191], v[96:99]
	v_mfma_f32_16x16x32_bf16 v[84:87], v[124:127], v[222:225], v[84:87]
	v_mfma_f32_16x16x32_bf16 v[80:83], v[132:135], v[222:225], v[80:83]
	v_mfma_f32_16x16x32_bf16 v[164:167], v[128:131], v[148:151], v[164:167]
	v_mfma_f32_16x16x32_bf16 v[160:163], v[136:139], v[148:151], v[160:163]
	v_mfma_f32_16x16x32_bf16 v[116:119], v[128:131], v[156:159], v[116:119]
	v_mfma_f32_16x16x32_bf16 v[112:115], v[136:139], v[156:159], v[112:115]
	v_mfma_f32_16x16x32_bf16 v[100:103], v[128:131], v[192:195], v[100:103]
	v_mfma_f32_16x16x32_bf16 v[96:99], v[136:139], v[192:195], v[96:99]
	v_mfma_f32_16x16x32_bf16 v[84:87], v[128:131], v[226:229], v[84:87]
	v_mfma_f32_16x16x32_bf16 v[80:83], v[136:139], v[226:229], v[80:83]
	s_barrier
	s_add_i32 m0, s57, 0x18000
	ds_read_b128 v[230:233], v217 offset:49152
	ds_read_b128 v[234:237], v217 offset:50176
	ds_read_b128 v[238:241], v217 offset:51200
	s_add_u32 s98, s52, 0x80
	s_addc_u32 s99, s53, 0
	global_load_lds_dwordx4 v0, s[98:99]
	s_add_i32 m0, s57, 0x1a000
	ds_read_b128 v[242:245], v217 offset:52224
	global_load_lds_dwordx4 v2, s[98:99]
	s_barrier
	s_waitcnt lgkmcnt(0)
	v_mfma_f32_16x16x32_bf16 v[144:147], v[230:233], v[140:143], v[144:147]
	v_mfma_f32_16x16x32_bf16 v[120:123], v[238:241], v[140:143], v[120:123]
	v_mfma_f32_16x16x32_bf16 v[108:111], v[230:233], v[152:155], v[108:111]
	v_mfma_f32_16x16x32_bf16 v[104:107], v[238:241], v[152:155], v[104:107]
	v_mfma_f32_16x16x32_bf16 v[92:95], v[230:233], v[188:191], v[92:95]
	v_mfma_f32_16x16x32_bf16 v[88:91], v[238:241], v[188:191], v[88:91]
	v_mfma_f32_16x16x32_bf16 v[76:79], v[230:233], v[222:225], v[76:79]
	v_mfma_f32_16x16x32_bf16 v[72:75], v[238:241], v[222:225], v[72:75]
	v_mfma_f32_16x16x32_bf16 v[144:147], v[234:237], v[148:151], v[144:147]
	v_mfma_f32_16x16x32_bf16 v[120:123], v[242:245], v[148:151], v[120:123]
	v_mfma_f32_16x16x32_bf16 v[108:111], v[234:237], v[156:159], v[108:111]
	v_mfma_f32_16x16x32_bf16 v[104:107], v[242:245], v[156:159], v[104:107]
	v_mfma_f32_16x16x32_bf16 v[92:95], v[234:237], v[192:195], v[92:95]
	v_mfma_f32_16x16x32_bf16 v[88:91], v[242:245], v[192:195], v[88:91]
	v_mfma_f32_16x16x32_bf16 v[76:79], v[234:237], v[226:229], v[76:79]
	v_mfma_f32_16x16x32_bf16 v[72:75], v[242:245], v[226:229], v[72:75]
	s_mov_b32 m0, s62
	s_barrier
	ds_read_b128 v[140:143], v186 offset:49152
	ds_read_b128 v[148:151], v186 offset:50176
	ds_read_b128 v[152:155], v186 offset:51200
	ds_read_b128 v[156:159], v186 offset:52224
	ds_read_b128 v[188:191], v186 offset:53248
	ds_read_b128 v[192:195], v186 offset:54272
	ds_read_b128 v[222:225], v186 offset:55296
	s_add_u32 s98, s54, 0xfffc0080
	s_addc_u32 s99, s55, -1
	global_load_lds_dwordx4 v0, s[98:99]
	s_mov_b32 m0, s63
	ds_read_b128 v[226:229], v186 offset:56320
	global_load_lds_dwordx4 v2, s[98:99]
	s_barrier
	s_waitcnt lgkmcnt(0)
	v_mfma_f32_16x16x32_bf16 v[60:63], v[124:127], v[140:143], v[60:63]
	v_mfma_f32_16x16x32_bf16 v[56:59], v[132:135], v[140:143], v[56:59]
	v_mfma_f32_16x16x32_bf16 v[44:47], v[124:127], v[152:155], v[44:47]
	v_mfma_f32_16x16x32_bf16 v[40:43], v[132:135], v[152:155], v[40:43]
	v_mfma_f32_16x16x32_bf16 v[28:31], v[124:127], v[188:191], v[28:31]
	v_mfma_f32_16x16x32_bf16 v[24:27], v[132:135], v[188:191], v[24:27]
	v_mfma_f32_16x16x32_bf16 v[12:15], v[124:127], v[222:225], v[12:15]
	v_mfma_f32_16x16x32_bf16 v[8:11], v[132:135], v[222:225], v[8:11]
	v_mfma_f32_16x16x32_bf16 v[60:63], v[128:131], v[148:151], v[60:63]
	v_mfma_f32_16x16x32_bf16 v[56:59], v[136:139], v[148:151], v[56:59]
	v_mfma_f32_16x16x32_bf16 v[44:47], v[128:131], v[156:159], v[44:47]
	v_mfma_f32_16x16x32_bf16 v[40:43], v[136:139], v[156:159], v[40:43]
	v_mfma_f32_16x16x32_bf16 v[28:31], v[128:131], v[192:195], v[28:31]
	v_mfma_f32_16x16x32_bf16 v[24:27], v[136:139], v[192:195], v[24:27]
	v_mfma_f32_16x16x32_bf16 v[12:15], v[128:131], v[226:229], v[12:15]
	v_mfma_f32_16x16x32_bf16 v[8:11], v[136:139], v[226:229], v[8:11]
	s_barrier
	s_add_i32 m0, s57, 0x1c000
	s_add_u32 s52, s52, 0x40080
	s_addc_u32 s53, s53, 0
	global_load_lds_dwordx4 v0, s[52:53]
	s_add_i32 m0, s57, 0x1e000
	s_add_i32 s73, s73, 2
	global_load_lds_dwordx4 v2, s[52:53]
	s_add_u32 s71, s71, 0x100
	s_addc_u32 s72, s72, 0
	s_add_u32 s50, s50, 0x100
	s_addc_u32 s51, s51, 0
	s_cmp_gt_u32 s73, 13
	s_cbranch_scc1 .LrotX_78
	s_add_u32 s12, s50, 0xfffc0080
	s_addc_u32 s26, s51, -1
	s_cmp_lg_u32 s73, 12
	s_cselect_b32 s55, s26, s43
	s_cselect_b32 s54, s12, s42
	s_cselect_b32 s53, s72, s15
	s_cselect_b32 s52, s71, s69
; #define G_MMA(ai, bj, At, Bt) do { __builtin_amdgcn_s_setprio(1); _Pragma("unroll") for (int m = 0; m < 4; ++m) _Pragma("unroll") for (int n = 0; n < 2; ++n) _Pragma("unroll") for (int k = 0; k < 2; ++k) \
;         acc[ai][bj][m][n] = MFMA16(Bt[n][k], At[m][k], acc[ai][bj][m][n]); __builtin_amdgcn_s_setprio(0); } while (0)
; #define G_WAIT_V(n) asm volatile("s_waitcnt vmcnt(" #n ")" ::: "memory")
; #define G_BAR __builtin_amdgcn_s_barrier()
; template <class Epi>
; __device__ __forceinline__ void gemm_phase(LAS unsigned char* lds, const bf16_t* Ag, const bf16_t* Btg, const int K, const int nM, const int nN, const Epi& E) {
;     ...
;             G_WAIT_V(6); G_BAR; G_MMA(1, 1, At, B1); G_BAR;
;         }
.LrotX_78:
	s_waitcnt vmcnt(6)
	s_barrier
	v_mfma_f32_16x16x32_bf16 v[68:71], v[230:233], v[140:143], v[68:71]
	v_mfma_f32_16x16x32_bf16 v[64:67], v[238:241], v[140:143], v[64:67]
	v_mfma_f32_16x16x32_bf16 v[52:55], v[230:233], v[152:155], v[52:55]
	v_mfma_f32_16x16x32_bf16 v[48:51], v[238:241], v[152:155], v[48:51]
	v_mfma_f32_16x16x32_bf16 v[36:39], v[230:233], v[188:191], v[36:39]
	v_mfma_f32_16x16x32_bf16 v[32:35], v[238:241], v[188:191], v[32:35]
	v_mfma_f32_16x16x32_bf16 v[20:23], v[230:233], v[222:225], v[20:23]
	v_mfma_f32_16x16x32_bf16 v[16:19], v[238:241], v[222:225], v[16:19]
	v_mfma_f32_16x16x32_bf16 v[68:71], v[234:237], v[148:151], v[68:71]
	v_mfma_f32_16x16x32_bf16 v[64:67], v[242:245], v[148:151], v[64:67]
	v_mfma_f32_16x16x32_bf16 v[52:55], v[234:237], v[156:159], v[52:55]
	v_mfma_f32_16x16x32_bf16 v[48:51], v[242:245], v[156:159], v[48:51]
	v_mfma_f32_16x16x32_bf16 v[36:39], v[234:237], v[192:195], v[36:39]
	v_mfma_f32_16x16x32_bf16 v[32:35], v[242:245], v[192:195], v[32:35]
	v_mfma_f32_16x16x32_bf16 v[20:23], v[234:237], v[226:229], v[20:23]
	v_mfma_f32_16x16x32_bf16 v[16:19], v[242:245], v[226:229], v[16:19]
	s_cmp_lt_u32 s73, 12
	s_barrier
	s_cbranch_scc1 .LmainW_78
	s_cmp_gt_u32 s73, 13
	s_cbranch_scc1 .LBB0_82

; #define G_STAGE(bufoff, gbase) do { _Pragma("unroll") for (int _i = 0; _i < 2; ++_i) \
;         __builtin_amdgcn_global_load_lds((const unsigned*)((const char*)(gbase) + voff[_i]), (LAS unsigned*)(lds + (bufoff) + ldsw + _i * 8192), 16, 0, 0); } while (0)
; #define G_LDA(dst, b, h) do { _Pragma("unroll") for (int m = 0; m < 4; ++m) _Pragma("unroll") for (int k = 0; k < 2; ++k) dst[m][k] = *(const LAS bf16x8*)(lds + G_SA(b, h) + aoff + m * 2048 + k * 1024); } while (0)
; #define G_LDB(dst, b, h) do { _Pragma("unroll") for (int n = 0; n < 2; ++n) _Pragma("unroll") for (int k = 0; k < 2; ++k) dst[n][k] = *(const LAS bf16x8*)(lds + G_SB(b, h) + boff + n * 2048 + k * 1024); } while (0)
; #define G_MMA(ai, bj, At, Bt) do { __builtin_amdgcn_s_setprio(1); _Pragma("unroll") for (int m = 0; m < 4; ++m) _Pragma("unroll") for (int n = 0; n < 2; ++n) _Pragma("unroll") for (int k = 0; k < 2; ++k) \
;         acc[ai][bj][m][n] = MFMA16(Bt[n][k], At[m][k], acc[ai][bj][m][n]); __builtin_amdgcn_s_setprio(0); } while (0)
; #define G_WAIT_V(n) asm volatile("s_waitcnt vmcnt(" #n ")" ::: "memory")
; #define G_WAIT_L(n) asm volatile("s_waitcnt lgkmcnt(" #n ")" ::: "memory")
; #define G_BAR __builtin_amdgcn_s_barrier()
; #define G_SCHED __builtin_amdgcn_sched_barrier(0)
; template <class Epi>
; __device__ __forceinline__ void gemm_phase(LAS unsigned char* lds, const bf16_t* Ag, const bf16_t* Btg, const int K, const int nM, const int nN, const Epi& E) {
;     ...
;             G_LDB(B0, 0, 0); G_SCHED; G_LDA(At, 0, 0); G_STAGE(G_SA(1, 1), a1 + hstep);
;             G_WAIT_L(8); G_BAR; G_WAIT_L(0); G_MMA(0, 0, At, B0); G_BAR; G_SCHED;
;             G_LDB(B1, 0, 1); G_STAGE(G_SB(0, 0), b2);
;             G_BAR; G_WAIT_L(0); G_MMA(0, 1, At, B1); G_BAR;
;             G_LDA(At, 0, 1); G_STAGE(G_SA(0, 0), a2);
;             G_BAR; G_WAIT_L(0); G_MMA(1, 0, At, B0); G_BAR; G_SCHED;
;             G_STAGE(G_SB(0, 1), b2 + hstep);
;             G_WAIT_V(6); G_BAR; G_MMA(1, 1, At, B1); G_BAR;
.LmainW_153:
	ds_read_b128 v[144:147], v217
	ds_read_b128 v[148:151], v217 offset:1024
	ds_read_b128 v[152:155], v217 offset:2048
	ds_read_b128 v[156:159], v217 offset:3072
	s_add_i32 m0, s72, 0xc000
	ds_read_b128 v[160:163], v230
	ds_read_b128 v[164:167], v230 offset:1024
	ds_read_b128 v[168:171], v230 offset:2048
	ds_read_b128 v[172:175], v230 offset:3072
	ds_read_b128 v[180:183], v230 offset:4096
	ds_read_b128 v[184:187], v230 offset:5120
	ds_read_b128 v[188:191], v230 offset:6144
	global_load_lds_dwordx4 v138, s[64:65]
	s_add_i32 m0, s72, 0xe000
	ds_read_b128 v[192:195], v230 offset:7168
	global_load_lds_dwordx4 v136, s[64:65]
	s_waitcnt lgkmcnt(8)
	s_barrier
	s_waitcnt lgkmcnt(0)
	v_mfma_f32_16x16x32_bf16 v[132:135], v[144:147], v[160:163], v[132:135]
	v_mfma_f32_16x16x32_bf16 v[128:131], v[152:155], v[160:163], v[128:131]
	v_mfma_f32_16x16x32_bf16 v[116:119], v[144:147], v[168:171], v[116:119]
	v_mfma_f32_16x16x32_bf16 v[112:115], v[152:155], v[168:171], v[112:115]
	v_mfma_f32_16x16x32_bf16 v[100:103], v[144:147], v[180:183], v[100:103]
	v_mfma_f32_16x16x32_bf16 v[96:99], v[152:155], v[180:183], v[96:99]
	v_mfma_f32_16x16x32_bf16 v[84:87], v[144:147], v[188:191], v[84:87]
	v_mfma_f32_16x16x32_bf16 v[80:83], v[152:155], v[188:191], v[80:83]
	v_mfma_f32_16x16x32_bf16 v[132:135], v[148:151], v[164:167], v[132:135]
	v_mfma_f32_16x16x32_bf16 v[128:131], v[156:159], v[164:167], v[128:131]
	v_mfma_f32_16x16x32_bf16 v[116:119], v[148:151], v[172:175], v[116:119]
	v_mfma_f32_16x16x32_bf16 v[112:115], v[156:159], v[172:175], v[112:115]
	v_mfma_f32_16x16x32_bf16 v[100:103], v[148:151], v[184:187], v[100:103]
	v_mfma_f32_16x16x32_bf16 v[96:99], v[156:159], v[184:187], v[96:99]
	v_mfma_f32_16x16x32_bf16 v[84:87], v[148:151], v[192:195], v[84:87]
	v_mfma_f32_16x16x32_bf16 v[80:83], v[156:159], v[192:195], v[80:83]
	s_barrier
	s_add_i32 m0, s21, 0x10000
	ds_read_b128 v[232:235], v217 offset:16384
	ds_read_b128 v[236:239], v217 offset:17408
	ds_read_b128 v[240:243], v217 offset:18432
	global_load_lds_dwordx4 v0, s[68:69]
	s_add_i32 m0, s21, 0x12000
	ds_read_b128 v[244:247], v217 offset:19456
	global_load_lds_dwordx4 v2, s[68:69]
	s_barrier
	s_waitcnt lgkmcnt(0)
	v_mfma_f32_16x16x32_bf16 v[124:127], v[232:235], v[160:163], v[124:127]
	v_mfma_f32_16x16x32_bf16 v[120:123], v[240:243], v[160:163], v[120:123]
	v_mfma_f32_16x16x32_bf16 v[108:111], v[232:235], v[168:171], v[108:111]
	v_mfma_f32_16x16x32_bf16 v[104:107], v[240:243], v[168:171], v[104:107]
	v_mfma_f32_16x16x32_bf16 v[92:95], v[232:235], v[180:183], v[92:95]
	v_mfma_f32_16x16x32_bf16 v[88:91], v[240:243], v[180:183], v[88:91]
	v_mfma_f32_16x16x32_bf16 v[76:79], v[232:235], v[188:191], v[76:79]
	v_mfma_f32_16x16x32_bf16 v[72:75], v[240:243], v[188:191], v[72:75]
	v_mfma_f32_16x16x32_bf16 v[124:127], v[236:239], v[164:167], v[124:127]
	v_mfma_f32_16x16x32_bf16 v[120:123], v[244:247], v[164:167], v[120:123]
	v_mfma_f32_16x16x32_bf16 v[108:111], v[236:239], v[172:175], v[108:111]
	v_mfma_f32_16x16x32_bf16 v[104:107], v[244:247], v[172:175], v[104:107]
	v_mfma_f32_16x16x32_bf16 v[92:95], v[236:239], v[184:187], v[92:95]
	v_mfma_f32_16x16x32_bf16 v[88:91], v[244:247], v[184:187], v[88:91]
	v_mfma_f32_16x16x32_bf16 v[76:79], v[236:239], v[192:195], v[76:79]
	v_mfma_f32_16x16x32_bf16 v[72:75], v[244:247], v[192:195], v[72:75]
	s_mov_b32 m0, s72
	s_barrier
	ds_read_b128 v[160:163], v230 offset:16384
	ds_read_b128 v[164:167], v230 offset:17408
	ds_read_b128 v[168:171], v230 offset:18432
	ds_read_b128 v[172:175], v230 offset:19456
	ds_read_b128 v[180:183], v230 offset:20480
	ds_read_b128 v[184:187], v230 offset:21504
	ds_read_b128 v[188:191], v230 offset:22528
	global_load_lds_dwordx4 v0, s[70:71]
	s_mov_b32 m0, s73
	ds_read_b128 v[192:195], v230 offset:23552
	global_load_lds_dwordx4 v2, s[70:71]
	s_barrier
	s_waitcnt lgkmcnt(0)
	v_mfma_f32_16x16x32_bf16 v[68:71], v[144:147], v[160:163], v[68:71]
	v_mfma_f32_16x16x32_bf16 v[64:67], v[152:155], v[160:163], v[64:67]
	v_mfma_f32_16x16x32_bf16 v[52:55], v[144:147], v[168:171], v[52:55]
	v_mfma_f32_16x16x32_bf16 v[48:51], v[152:155], v[168:171], v[48:51]
	v_mfma_f32_16x16x32_bf16 v[36:39], v[144:147], v[180:183], v[36:39]
	v_mfma_f32_16x16x32_bf16 v[32:35], v[152:155], v[180:183], v[32:35]
	v_mfma_f32_16x16x32_bf16 v[20:23], v[144:147], v[188:191], v[20:23]
	v_mfma_f32_16x16x32_bf16 v[16:19], v[152:155], v[188:191], v[16:19]
	v_mfma_f32_16x16x32_bf16 v[68:71], v[148:151], v[164:167], v[68:71]
	v_mfma_f32_16x16x32_bf16 v[64:67], v[156:159], v[164:167], v[64:67]
	v_mfma_f32_16x16x32_bf16 v[52:55], v[148:151], v[172:175], v[52:55]
	v_mfma_f32_16x16x32_bf16 v[48:51], v[156:159], v[172:175], v[48:51]
	v_mfma_f32_16x16x32_bf16 v[36:39], v[148:151], v[184:187], v[36:39]
	v_mfma_f32_16x16x32_bf16 v[32:35], v[156:159], v[184:187], v[32:35]
	v_mfma_f32_16x16x32_bf16 v[20:23], v[148:151], v[192:195], v[20:23]
	v_mfma_f32_16x16x32_bf16 v[16:19], v[156:159], v[192:195], v[16:19]
	s_barrier
	s_add_i32 m0, s21, 0x14000
	s_add_u32 s64, s68, 0x40000
	s_addc_u32 s65, s69, 0
	global_load_lds_dwordx4 v0, s[64:65]
	s_add_i32 m0, s21, 0x16000
	s_add_u32 s98, s70, 0x40000
	s_addc_u32 s99, s71, 0
	global_load_lds_dwordx4 v2, s[64:65]
	s_waitcnt vmcnt(6)
	s_barrier
;     __device__ __forceinline__ void prep(int pm, int par, LAS unsigned char* lds) const { if (fold) prep_rowstats(stat, pm, par, lds); }
;     __device__ __forceinline__ void prep(int pm, int par, LAS unsigned char* lds) const { if (!ident) prep_rowstats(stat, pm, par, lds); }
;     __device__ __forceinline__ void prep(int pm, int par, LAS unsigned char* lds) const { prep_rowstats(stat, pm, par, lds); }
; #define G_STAGE(bufoff, gbase) do { _Pragma("unroll") for (int _i = 0; _i < 2; ++_i) \
;         __builtin_amdgcn_global_load_lds((const unsigned*)((const char*)(gbase) + voff[_i]), (LAS unsigned*)(lds + (bufoff) + ldsw + _i * 8192), 16, 0, 0); } while (0)
; #define G_WAIT_V(n) asm volatile("s_waitcnt vmcnt(" #n ")" ::: "memory")
; #define G_BAR __builtin_amdgcn_s_barrier()
; template <class Epi>
; __device__ __forceinline__ void gemm_phase(LAS unsigned char* lds, const bf16_t* Ag, const bf16_t* Btg, const int K, const int nM, const int nN, const Epi& E) {
;     ...
;         for (int t = 0; t < nt; t += 2) {
;             const bool last = (t == nt - 2);
;             const char* a1 = cA + (size_t)(t + 1) * kstep;
;             const char* a2 = last ? nA : cA + (size_t)(t + 2) * kstep; const char* b2 = last ? nB : cB + (size_t)(t + 2) * kstep;
;             const char* a3 = a2 + kstep; const char* b3 = b2 + kstep;
;             if (last && has_next && pmn != pm) E.prep(pmn, par ^ 1, lds);
;             G_LDB(B0, 0, 0); G_SCHED; G_LDA(At, 0, 0); G_STAGE(G_SA(1, 1), a1 + hstep);
;             G_WAIT_L(8); G_BAR; G_WAIT_L(0); G_MMA(0, 0, At, B0); G_BAR; G_SCHED;
;             G_LDB(B1, 0, 1); G_STAGE(G_SB(0, 0), b2);
;             G_BAR; G_WAIT_L(0); G_MMA(0, 1, At, B1); G_BAR;
;             G_LDA(At, 0, 1); G_STAGE(G_SA(0, 0), a2);
;             G_BAR; G_WAIT_L(0); G_MMA(1, 0, At, B0); G_BAR; G_SCHED;
;             G_STAGE(G_SB(0, 1), b2 + hstep);
;             G_WAIT_V(6); G_BAR; G_MMA(1, 1, At, B1); G_BAR;
;             G_LDB(B0, 1, 0); G_SCHED; G_LDA(At, 1, 0); G_STAGE(G_SA(0, 1), a2 + hstep);
;             G_WAIT_L(8); G_BAR; G_WAIT_L(0); G_MMA(0, 0, At, B0); G_BAR; G_SCHED;
;             G_LDB(B1, 1, 1); G_STAGE(G_SB(1, 0), b3);
;             G_BAR; G_WAIT_L(0); G_MMA(0, 1, At, B1); G_BAR;
;             G_LDA(At, 1, 1); G_STAGE(G_SA(1, 0), a3);
;             G_BAR; G_WAIT_L(0); G_MMA(1, 0, At, B0); G_BAR; G_SCHED;
;             G_STAGE(G_SB(1, 1), b3 + hstep);
	v_mfma_f32_16x16x32_bf16 v[60:63], v[232:235], v[160:163], v[60:63]
	v_mfma_f32_16x16x32_bf16 v[56:59], v[240:243], v[160:163], v[56:59]
	v_mfma_f32_16x16x32_bf16 v[44:47], v[232:235], v[168:171], v[44:47]
	v_mfma_f32_16x16x32_bf16 v[40:43], v[240:243], v[168:171], v[40:43]
	v_mfma_f32_16x16x32_bf16 v[28:31], v[232:235], v[180:183], v[28:31]
	v_mfma_f32_16x16x32_bf16 v[24:27], v[240:243], v[180:183], v[24:27]
	v_mfma_f32_16x16x32_bf16 v[12:15], v[232:235], v[188:191], v[12:15]
	v_mfma_f32_16x16x32_bf16 v[8:11], v[240:243], v[188:191], v[8:11]
	v_mfma_f32_16x16x32_bf16 v[60:63], v[236:239], v[164:167], v[60:63]
	v_mfma_f32_16x16x32_bf16 v[56:59], v[244:247], v[164:167], v[56:59]
	v_mfma_f32_16x16x32_bf16 v[44:47], v[236:239], v[172:175], v[44:47]
	v_mfma_f32_16x16x32_bf16 v[40:43], v[244:247], v[172:175], v[40:43]
	v_mfma_f32_16x16x32_bf16 v[28:31], v[236:239], v[184:187], v[28:31]
	v_mfma_f32_16x16x32_bf16 v[24:27], v[244:247], v[184:187], v[24:27]
	v_mfma_f32_16x16x32_bf16 v[12:15], v[236:239], v[192:195], v[12:15]
	v_mfma_f32_16x16x32_bf16 v[8:11], v[244:247], v[192:195], v[8:11]
	s_barrier
	ds_read_b128 v[144:147], v217 offset:32768
	ds_read_b128 v[148:151], v217 offset:33792
	ds_read_b128 v[152:155], v217 offset:34816
	ds_read_b128 v[156:159], v217 offset:35840
	s_mov_b32 m0, s74
	ds_read_b128 v[160:163], v230 offset:32768
	ds_read_b128 v[164:167], v230 offset:33792
	ds_read_b128 v[168:171], v230 offset:34816
	ds_read_b128 v[172:175], v230 offset:35840
	ds_read_b128 v[180:183], v230 offset:36864
	ds_read_b128 v[184:187], v230 offset:37888
	ds_read_b128 v[188:191], v230 offset:38912
	global_load_lds_dwordx4 v0, s[98:99]
	s_mov_b32 m0, s75
	ds_read_b128 v[192:195], v230 offset:39936
	global_load_lds_dwordx4 v2, s[98:99]
	s_waitcnt lgkmcnt(8)
	s_barrier
	s_waitcnt lgkmcnt(0)
	v_mfma_f32_16x16x32_bf16 v[132:135], v[144:147], v[160:163], v[132:135]
	v_mfma_f32_16x16x32_bf16 v[128:131], v[152:155], v[160:163], v[128:131]
	v_mfma_f32_16x16x32_bf16 v[116:119], v[144:147], v[168:171], v[116:119]
	v_mfma_f32_16x16x32_bf16 v[112:115], v[152:155], v[168:171], v[112:115]
	v_mfma_f32_16x16x32_bf16 v[100:103], v[144:147], v[180:183], v[100:103]
	v_mfma_f32_16x16x32_bf16 v[96:99], v[152:155], v[180:183], v[96:99]
	v_mfma_f32_16x16x32_bf16 v[84:87], v[144:147], v[188:191], v[84:87]
	v_mfma_f32_16x16x32_bf16 v[80:83], v[152:155], v[188:191], v[80:83]
	v_mfma_f32_16x16x32_bf16 v[132:135], v[148:151], v[164:167], v[132:135]
	v_mfma_f32_16x16x32_bf16 v[128:131], v[156:159], v[164:167], v[128:131]
	v_mfma_f32_16x16x32_bf16 v[116:119], v[148:151], v[172:175], v[116:119]
	v_mfma_f32_16x16x32_bf16 v[112:115], v[156:159], v[172:175], v[112:115]
	v_mfma_f32_16x16x32_bf16 v[100:103], v[148:151], v[184:187], v[100:103]
	v_mfma_f32_16x16x32_bf16 v[96:99], v[156:159], v[184:187], v[96:99]
	v_mfma_f32_16x16x32_bf16 v[84:87], v[148:151], v[192:195], v[84:87]
	v_mfma_f32_16x16x32_bf16 v[80:83], v[156:159], v[192:195], v[80:83]
	s_barrier
	s_add_i32 m0, s21, 0x18000
	ds_read_b128 v[232:235], v217 offset:49152
	ds_read_b128 v[236:239], v217 offset:50176
	ds_read_b128 v[240:243], v217 offset:51200
	s_add_u32 s98, s68, 0x80
	s_addc_u32 s99, s69, 0
	global_load_lds_dwordx4 v0, s[98:99]
	s_add_i32 m0, s21, 0x1a000
	ds_read_b128 v[244:247], v217 offset:52224
	global_load_lds_dwordx4 v2, s[98:99]
	s_barrier
	s_waitcnt lgkmcnt(0)
	v_mfma_f32_16x16x32_bf16 v[124:127], v[232:235], v[160:163], v[124:127]
	v_mfma_f32_16x16x32_bf16 v[120:123], v[240:243], v[160:163], v[120:123]
	v_mfma_f32_16x16x32_bf16 v[108:111], v[232:235], v[168:171], v[108:111]
	v_mfma_f32_16x16x32_bf16 v[104:107], v[240:243], v[168:171], v[104:107]
	v_mfma_f32_16x16x32_bf16 v[92:95], v[232:235], v[180:183], v[92:95]
	v_mfma_f32_16x16x32_bf16 v[88:91], v[240:243], v[180:183], v[88:91]
	v_mfma_f32_16x16x32_bf16 v[76:79], v[232:235], v[188:191], v[76:79]
	v_mfma_f32_16x16x32_bf16 v[72:75], v[240:243], v[188:191], v[72:75]
	v_mfma_f32_16x16x32_bf16 v[124:127], v[236:239], v[164:167], v[124:127]
	v_mfma_f32_16x16x32_bf16 v[120:123], v[244:247], v[164:167], v[120:123]
	v_mfma_f32_16x16x32_bf16 v[108:111], v[236:239], v[172:175], v[108:111]
	v_mfma_f32_16x16x32_bf16 v[104:107], v[244:247], v[172:175], v[104:107]
	v_mfma_f32_16x16x32_bf16 v[92:95], v[236:239], v[184:187], v[92:95]
	v_mfma_f32_16x16x32_bf16 v[88:91], v[244:247], v[184:187], v[88:91]
	v_mfma_f32_16x16x32_bf16 v[76:79], v[236:239], v[192:195], v[76:79]
	v_mfma_f32_16x16x32_bf16 v[72:75], v[244:247], v[192:195], v[72:75]
	s_mov_b32 m0, s76
	s_barrier
	ds_read_b128 v[160:163], v230 offset:49152
	ds_read_b128 v[164:167], v230 offset:50176
	ds_read_b128 v[168:171], v230 offset:51200
	ds_read_b128 v[172:175], v230 offset:52224
	ds_read_b128 v[180:183], v230 offset:53248
	ds_read_b128 v[184:187], v230 offset:54272
	ds_read_b128 v[188:191], v230 offset:55296
	s_add_u32 s98, s70, 0x80
	s_addc_u32 s99, s71, 0
	global_load_lds_dwordx4 v0, s[98:99]
	s_mov_b32 m0, s77
	ds_read_b128 v[192:195], v230 offset:56320
	global_load_lds_dwordx4 v2, s[98:99]
	s_barrier
	s_waitcnt lgkmcnt(0)
	v_mfma_f32_16x16x32_bf16 v[68:71], v[144:147], v[160:163], v[68:71]
	v_mfma_f32_16x16x32_bf16 v[64:67], v[152:155], v[160:163], v[64:67]
	v_mfma_f32_16x16x32_bf16 v[52:55], v[144:147], v[168:171], v[52:55]
	v_mfma_f32_16x16x32_bf16 v[48:51], v[152:155], v[168:171], v[48:51]
	v_mfma_f32_16x16x32_bf16 v[36:39], v[144:147], v[180:183], v[36:39]
	v_mfma_f32_16x16x32_bf16 v[32:35], v[152:155], v[180:183], v[32:35]
	v_mfma_f32_16x16x32_bf16 v[20:23], v[144:147], v[188:191], v[20:23]
	v_mfma_f32_16x16x32_bf16 v[16:19], v[152:155], v[188:191], v[16:19]
	v_mfma_f32_16x16x32_bf16 v[68:71], v[148:151], v[164:167], v[68:71]
	v_mfma_f32_16x16x32_bf16 v[64:67], v[156:159], v[164:167], v[64:67]
	v_mfma_f32_16x16x32_bf16 v[52:55], v[148:151], v[172:175], v[52:55]
	v_mfma_f32_16x16x32_bf16 v[48:51], v[156:159], v[172:175], v[48:51]
	v_mfma_f32_16x16x32_bf16 v[36:39], v[148:151], v[184:187], v[36:39]
	v_mfma_f32_16x16x32_bf16 v[32:35], v[156:159], v[184:187], v[32:35]
	v_mfma_f32_16x16x32_bf16 v[20:23], v[148:151], v[192:195], v[20:23]
	v_mfma_f32_16x16x32_bf16 v[16:19], v[156:159], v[192:195], v[16:19]
	s_barrier
	s_add_i32 m0, s21, 0x1c000
	s_add_u32 s64, s68, 0x40080
	s_addc_u32 s65, s69, 0
	global_load_lds_dwordx4 v0, s[64:65]
	s_add_i32 m0, s21, 0x1e000
	s_add_i32 s42, s42, 2
	global_load_lds_dwordx4 v2, s[64:65]
	s_add_u32 s57, s57, 0x100
	s_addc_u32 s61, s61, 0
	s_mov_b64 s[64:65], s[66:67]
	s_cmp_gt_u32 s42, 13
	s_cbranch_scc1 .LrotX_153
	s_add_u32 s66, s64, 0x100
	s_addc_u32 s67, s65, 0
	s_cmp_lg_u32 s42, 12
	s_cselect_b32 s71, s67, s55
	s_cselect_b32 s70, s66, s54
	s_cselect_b32 s69, s61, s14
	s_cselect_b32 s68, s57, s15
; #define G_MMA(ai, bj, At, Bt) do { __builtin_amdgcn_s_setprio(1); _Pragma("unroll") for (int m = 0; m < 4; ++m) _Pragma("unroll") for (int n = 0; n < 2; ++n) _Pragma("unroll") for (int k = 0; k < 2; ++k) \
;         acc[ai][bj][m][n] = MFMA16(Bt[n][k], At[m][k], acc[ai][bj][m][n]); __builtin_amdgcn_s_setprio(0); } while (0)
; #define G_WAIT_V(n) asm volatile("s_waitcnt vmcnt(" #n ")" ::: "memory")
; #define G_BAR __builtin_amdgcn_s_barrier()
; template <class Epi>
; __device__ __forceinline__ void gemm_phase(LAS unsigned char* lds, const bf16_t* Ag, const bf16_t* Btg, const int K, const int nM, const int nN, const Epi& E) {
;     ...
;             G_WAIT_V(6); G_BAR; G_MMA(1, 1, At, B1); G_BAR;
;         }
.LrotX_153:
	s_waitcnt vmcnt(6)
	s_barrier
	v_mfma_f32_16x16x32_bf16 v[60:63], v[232:235], v[160:163], v[60:63]
	v_mfma_f32_16x16x32_bf16 v[56:59], v[240:243], v[160:163], v[56:59]
	v_mfma_f32_16x16x32_bf16 v[44:47], v[232:235], v[168:171], v[44:47]
	v_mfma_f32_16x16x32_bf16 v[40:43], v[240:243], v[168:171], v[40:43]
	v_mfma_f32_16x16x32_bf16 v[28:31], v[232:235], v[180:183], v[28:31]
	v_mfma_f32_16x16x32_bf16 v[24:27], v[240:243], v[180:183], v[24:27]
	v_mfma_f32_16x16x32_bf16 v[12:15], v[232:235], v[188:191], v[12:15]
	v_mfma_f32_16x16x32_bf16 v[8:11], v[240:243], v[188:191], v[8:11]
	v_mfma_f32_16x16x32_bf16 v[60:63], v[236:239], v[164:167], v[60:63]
	v_mfma_f32_16x16x32_bf16 v[56:59], v[244:247], v[164:167], v[56:59]
	v_mfma_f32_16x16x32_bf16 v[44:47], v[236:239], v[172:175], v[44:47]
	v_mfma_f32_16x16x32_bf16 v[40:43], v[244:247], v[172:175], v[40:43]
	v_mfma_f32_16x16x32_bf16 v[28:31], v[236:239], v[184:187], v[28:31]
	v_mfma_f32_16x16x32_bf16 v[24:27], v[244:247], v[184:187], v[24:27]
	v_mfma_f32_16x16x32_bf16 v[12:15], v[236:239], v[192:195], v[12:15]
	v_mfma_f32_16x16x32_bf16 v[8:11], v[244:247], v[192:195], v[8:11]
	s_cmp_lt_u32 s42, 12
	s_barrier
	s_cbranch_scc1 .LmainW_153
	s_cmp_gt_u32 s42, 13
	s_cbranch_scc1 .LBB0_157

; #define G_STAGE(bufoff, gbase) do { _Pragma("unroll") for (int _i = 0; _i < 2; ++_i) \
;         __builtin_amdgcn_global_load_lds((const unsigned*)((const char*)(gbase) + voff[_i]), (LAS unsigned*)(lds + (bufoff) + ldsw + _i * 8192), 16, 0, 0); } while (0)
; #define G_LDA(dst, b, h) do { _Pragma("unroll") for (int m = 0; m < 4; ++m) _Pragma("unroll") for (int k = 0; k < 2; ++k) dst[m][k] = *(const LAS bf16x8*)(lds + G_SA(b, h) + aoff + m * 2048 + k * 1024); } while (0)
; #define G_LDB(dst, b, h) do { _Pragma("unroll") for (int n = 0; n < 2; ++n) _Pragma("unroll") for (int k = 0; k < 2; ++k) dst[n][k] = *(const LAS bf16x8*)(lds + G_SB(b, h) + boff + n * 2048 + k * 1024); } while (0)
; #define G_MMA(ai, bj, At, Bt) do { __builtin_amdgcn_s_setprio(1); _Pragma("unroll") for (int m = 0; m < 4; ++m) _Pragma("unroll") for (int n = 0; n < 2; ++n) _Pragma("unroll") for (int k = 0; k < 2; ++k) \
;         acc[ai][bj][m][n] = MFMA16(Bt[n][k], At[m][k], acc[ai][bj][m][n]); __builtin_amdgcn_s_setprio(0); } while (0)
; #define G_WAIT_V(n) asm volatile("s_waitcnt vmcnt(" #n ")" ::: "memory")
; #define G_WAIT_L(n) asm volatile("s_waitcnt lgkmcnt(" #n ")" ::: "memory")
; #define G_BAR __builtin_amdgcn_s_barrier()
; #define G_SCHED __builtin_amdgcn_sched_barrier(0)
; template <class Epi>
; __device__ __forceinline__ void gemm_phase(LAS unsigned char* lds, const bf16_t* Ag, const bf16_t* Btg, const int K, const int nM, const int nN, const Epi& E) {
;     ...
;             G_LDB(B0, 0, 0); G_SCHED; G_LDA(At, 0, 0); G_STAGE(G_SA(1, 1), a1 + hstep);
;             G_WAIT_L(8); G_BAR; G_WAIT_L(0); G_MMA(0, 0, At, B0); G_BAR; G_SCHED;
;             G_LDB(B1, 0, 1); G_STAGE(G_SB(0, 0), b2);
;             G_BAR; G_WAIT_L(0); G_MMA(0, 1, At, B1); G_BAR;
;             G_LDA(At, 0, 1); G_STAGE(G_SA(0, 0), a2);
;             G_BAR; G_WAIT_L(0); G_MMA(1, 0, At, B0); G_BAR; G_SCHED;
;             G_STAGE(G_SB(0, 1), b2 + hstep);
;             G_WAIT_V(6); G_BAR; G_MMA(1, 1, At, B1); G_BAR;
.LmainW_744:
	ds_read_b128 v[140:143], v217
	ds_read_b128 v[144:147], v217 offset:1024
	ds_read_b128 v[148:151], v217 offset:2048
	ds_read_b128 v[152:155], v217 offset:3072
	s_add_i32 m0, s66, 0xc000
	ds_read_b128 v[156:159], v174
	ds_read_b128 v[160:163], v174 offset:1024
	ds_read_b128 v[180:183], v174 offset:2048
	ds_read_b128 v[184:187], v174 offset:3072
	ds_read_b128 v[188:191], v174 offset:4096
	ds_read_b128 v[192:195], v174 offset:5120
	ds_read_b128 v[222:225], v174 offset:6144
	global_load_lds_dwordx4 v138, s[56:57]
	s_add_i32 m0, s66, 0xe000
	ds_read_b128 v[226:229], v174 offset:7168
	global_load_lds_dwordx4 v136, s[56:57]
	s_waitcnt lgkmcnt(8)
	s_barrier
	s_waitcnt lgkmcnt(0)
	v_mfma_f32_16x16x32_bf16 v[132:135], v[140:143], v[156:159], v[132:135]
	v_mfma_f32_16x16x32_bf16 v[128:131], v[148:151], v[156:159], v[128:131]
	v_mfma_f32_16x16x32_bf16 v[116:119], v[140:143], v[180:183], v[116:119]
	v_mfma_f32_16x16x32_bf16 v[112:115], v[148:151], v[180:183], v[112:115]
	v_mfma_f32_16x16x32_bf16 v[100:103], v[140:143], v[188:191], v[100:103]
	v_mfma_f32_16x16x32_bf16 v[96:99], v[148:151], v[188:191], v[96:99]
	v_mfma_f32_16x16x32_bf16 v[84:87], v[140:143], v[222:225], v[84:87]
	v_mfma_f32_16x16x32_bf16 v[80:83], v[148:151], v[222:225], v[80:83]
	v_mfma_f32_16x16x32_bf16 v[132:135], v[144:147], v[160:163], v[132:135]
	v_mfma_f32_16x16x32_bf16 v[128:131], v[152:155], v[160:163], v[128:131]
	v_mfma_f32_16x16x32_bf16 v[116:119], v[144:147], v[184:187], v[116:119]
	v_mfma_f32_16x16x32_bf16 v[112:115], v[152:155], v[184:187], v[112:115]
	v_mfma_f32_16x16x32_bf16 v[100:103], v[144:147], v[192:195], v[100:103]
	v_mfma_f32_16x16x32_bf16 v[96:99], v[152:155], v[192:195], v[96:99]
	v_mfma_f32_16x16x32_bf16 v[84:87], v[144:147], v[226:229], v[84:87]
	v_mfma_f32_16x16x32_bf16 v[80:83], v[152:155], v[226:229], v[80:83]
	s_barrier
	s_add_i32 m0, s65, 0x10000
	ds_read_b128 v[230:233], v217 offset:16384
	ds_read_b128 v[234:237], v217 offset:17408
	ds_read_b128 v[238:241], v217 offset:18432
	global_load_lds_dwordx4 v0, s[60:61]
	s_add_i32 m0, s65, 0x12000
	ds_read_b128 v[242:245], v217 offset:19456
	global_load_lds_dwordx4 v2, s[60:61]
	s_barrier
	s_waitcnt lgkmcnt(0)
	v_mfma_f32_16x16x32_bf16 v[124:127], v[230:233], v[156:159], v[124:127]
	v_mfma_f32_16x16x32_bf16 v[120:123], v[238:241], v[156:159], v[120:123]
	v_mfma_f32_16x16x32_bf16 v[108:111], v[230:233], v[180:183], v[108:111]
	v_mfma_f32_16x16x32_bf16 v[104:107], v[238:241], v[180:183], v[104:107]
	v_mfma_f32_16x16x32_bf16 v[92:95], v[230:233], v[188:191], v[92:95]
	v_mfma_f32_16x16x32_bf16 v[88:91], v[238:241], v[188:191], v[88:91]
	v_mfma_f32_16x16x32_bf16 v[76:79], v[230:233], v[222:225], v[76:79]
	v_mfma_f32_16x16x32_bf16 v[72:75], v[238:241], v[222:225], v[72:75]
	v_mfma_f32_16x16x32_bf16 v[124:127], v[234:237], v[160:163], v[124:127]
	v_mfma_f32_16x16x32_bf16 v[120:123], v[242:245], v[160:163], v[120:123]
	v_mfma_f32_16x16x32_bf16 v[108:111], v[234:237], v[184:187], v[108:111]
	v_mfma_f32_16x16x32_bf16 v[104:107], v[242:245], v[184:187], v[104:107]
	v_mfma_f32_16x16x32_bf16 v[92:95], v[234:237], v[192:195], v[92:95]
	v_mfma_f32_16x16x32_bf16 v[88:91], v[242:245], v[192:195], v[88:91]
	v_mfma_f32_16x16x32_bf16 v[76:79], v[234:237], v[226:229], v[76:79]
	v_mfma_f32_16x16x32_bf16 v[72:75], v[242:245], v[226:229], v[72:75]
	s_mov_b32 m0, s66
	s_barrier
	ds_read_b128 v[156:159], v174 offset:16384
	ds_read_b128 v[160:163], v174 offset:17408
	ds_read_b128 v[180:183], v174 offset:18432
	ds_read_b128 v[184:187], v174 offset:19456
	ds_read_b128 v[188:191], v174 offset:20480
	ds_read_b128 v[192:195], v174 offset:21504
	ds_read_b128 v[222:225], v174 offset:22528
	global_load_lds_dwordx4 v0, s[62:63]
	s_mov_b32 m0, s67
	ds_read_b128 v[226:229], v174 offset:23552
	global_load_lds_dwordx4 v2, s[62:63]
	s_barrier
	s_waitcnt lgkmcnt(0)
	v_mfma_f32_16x16x32_bf16 v[68:71], v[140:143], v[156:159], v[68:71]
	v_mfma_f32_16x16x32_bf16 v[64:67], v[148:151], v[156:159], v[64:67]
	v_mfma_f32_16x16x32_bf16 v[52:55], v[140:143], v[180:183], v[52:55]
	v_mfma_f32_16x16x32_bf16 v[48:51], v[148:151], v[180:183], v[48:51]
	v_mfma_f32_16x16x32_bf16 v[36:39], v[140:143], v[188:191], v[36:39]
	v_mfma_f32_16x16x32_bf16 v[32:35], v[148:151], v[188:191], v[32:35]
	v_mfma_f32_16x16x32_bf16 v[20:23], v[140:143], v[222:225], v[20:23]
	v_mfma_f32_16x16x32_bf16 v[16:19], v[148:151], v[222:225], v[16:19]
	v_mfma_f32_16x16x32_bf16 v[68:71], v[144:147], v[160:163], v[68:71]
	v_mfma_f32_16x16x32_bf16 v[64:67], v[152:155], v[160:163], v[64:67]
	v_mfma_f32_16x16x32_bf16 v[52:55], v[144:147], v[184:187], v[52:55]
	v_mfma_f32_16x16x32_bf16 v[48:51], v[152:155], v[184:187], v[48:51]
	v_mfma_f32_16x16x32_bf16 v[36:39], v[144:147], v[192:195], v[36:39]
	v_mfma_f32_16x16x32_bf16 v[32:35], v[152:155], v[192:195], v[32:35]
	v_mfma_f32_16x16x32_bf16 v[20:23], v[144:147], v[226:229], v[20:23]
	v_mfma_f32_16x16x32_bf16 v[16:19], v[152:155], v[226:229], v[16:19]
	s_barrier
	s_add_i32 m0, s65, 0x14000
	s_add_u32 s56, s60, 0x100000
	s_addc_u32 s57, s61, 0
	global_load_lds_dwordx4 v0, s[56:57]
	s_add_i32 m0, s65, 0x16000
	s_add_u32 s98, s62, 0x100000
	s_addc_u32 s99, s63, 0
	global_load_lds_dwordx4 v2, s[56:57]
	s_waitcnt vmcnt(6)
	s_barrier
;     __device__ __forceinline__ void prep(int pm, int par, LAS unsigned char* lds) const { if (fold) prep_rowstats(stat, pm, par, lds); }
;     __device__ __forceinline__ void prep(int pm, int par, LAS unsigned char* lds) const { if (!ident) prep_rowstats(stat, pm, par, lds); }
;     __device__ __forceinline__ void prep(int pm, int par, LAS unsigned char* lds) const { prep_rowstats(stat, pm, par, lds); }
; #define G_STAGE(bufoff, gbase) do { _Pragma("unroll") for (int _i = 0; _i < 2; ++_i) \
;         __builtin_amdgcn_global_load_lds((const unsigned*)((const char*)(gbase) + voff[_i]), (LAS unsigned*)(lds + (bufoff) + ldsw + _i * 8192), 16, 0, 0); } while (0)
; #define G_WAIT_V(n) asm volatile("s_waitcnt vmcnt(" #n ")" ::: "memory")
; #define G_BAR __builtin_amdgcn_s_barrier()
; template <class Epi>
; __device__ __forceinline__ void gemm_phase(LAS unsigned char* lds, const bf16_t* Ag, const bf16_t* Btg, const int K, const int nM, const int nN, const Epi& E) {
;     ...
;         for (int t = 0; t < nt; t += 2) {
;             const bool last = (t == nt - 2);
;             const char* a1 = cA + (size_t)(t + 1) * kstep;
;             const char* a2 = last ? nA : cA + (size_t)(t + 2) * kstep; const char* b2 = last ? nB : cB + (size_t)(t + 2) * kstep;
;             const char* a3 = a2 + kstep; const char* b3 = b2 + kstep;
;             if (last && has_next && pmn != pm) E.prep(pmn, par ^ 1, lds);
;             G_LDB(B0, 0, 0); G_SCHED; G_LDA(At, 0, 0); G_STAGE(G_SA(1, 1), a1 + hstep);
;             G_WAIT_L(8); G_BAR; G_WAIT_L(0); G_MMA(0, 0, At, B0); G_BAR; G_SCHED;
;             G_LDB(B1, 0, 1); G_STAGE(G_SB(0, 0), b2);
;             G_BAR; G_WAIT_L(0); G_MMA(0, 1, At, B1); G_BAR;
;             G_LDA(At, 0, 1); G_STAGE(G_SA(0, 0), a2);
;             G_BAR; G_WAIT_L(0); G_MMA(1, 0, At, B0); G_BAR; G_SCHED;
;             G_STAGE(G_SB(0, 1), b2 + hstep);
;             G_WAIT_V(6); G_BAR; G_MMA(1, 1, At, B1); G_BAR;
;             G_LDB(B0, 1, 0); G_SCHED; G_LDA(At, 1, 0); G_STAGE(G_SA(0, 1), a2 + hstep);
;             G_WAIT_L(8); G_BAR; G_WAIT_L(0); G_MMA(0, 0, At, B0); G_BAR; G_SCHED;
;             G_LDB(B1, 1, 1); G_STAGE(G_SB(1, 0), b3);
;             G_BAR; G_WAIT_L(0); G_MMA(0, 1, At, B1); G_BAR;
;             G_LDA(At, 1, 1); G_STAGE(G_SA(1, 0), a3);
;             G_BAR; G_WAIT_L(0); G_MMA(1, 0, At, B0); G_BAR; G_SCHED;
;             G_STAGE(G_SB(1, 1), b3 + hstep);
	v_mfma_f32_16x16x32_bf16 v[60:63], v[230:233], v[156:159], v[60:63]
	v_mfma_f32_16x16x32_bf16 v[56:59], v[238:241], v[156:159], v[56:59]
	v_mfma_f32_16x16x32_bf16 v[44:47], v[230:233], v[180:183], v[44:47]
	v_mfma_f32_16x16x32_bf16 v[40:43], v[238:241], v[180:183], v[40:43]
	v_mfma_f32_16x16x32_bf16 v[28:31], v[230:233], v[188:191], v[28:31]
	v_mfma_f32_16x16x32_bf16 v[24:27], v[238:241], v[188:191], v[24:27]
	v_mfma_f32_16x16x32_bf16 v[12:15], v[230:233], v[222:225], v[12:15]
	v_mfma_f32_16x16x32_bf16 v[8:11], v[238:241], v[222:225], v[8:11]
	v_mfma_f32_16x16x32_bf16 v[60:63], v[234:237], v[160:163], v[60:63]
	v_mfma_f32_16x16x32_bf16 v[56:59], v[242:245], v[160:163], v[56:59]
	v_mfma_f32_16x16x32_bf16 v[44:47], v[234:237], v[184:187], v[44:47]
	v_mfma_f32_16x16x32_bf16 v[40:43], v[242:245], v[184:187], v[40:43]
	v_mfma_f32_16x16x32_bf16 v[28:31], v[234:237], v[192:195], v[28:31]
	v_mfma_f32_16x16x32_bf16 v[24:27], v[242:245], v[192:195], v[24:27]
	v_mfma_f32_16x16x32_bf16 v[12:15], v[234:237], v[226:229], v[12:15]
	v_mfma_f32_16x16x32_bf16 v[8:11], v[242:245], v[226:229], v[8:11]
	s_barrier
	ds_read_b128 v[140:143], v217 offset:32768
	ds_read_b128 v[144:147], v217 offset:33792
	ds_read_b128 v[148:151], v217 offset:34816
	ds_read_b128 v[152:155], v217 offset:35840
	s_mov_b32 m0, s68
	ds_read_b128 v[156:159], v174 offset:32768
	ds_read_b128 v[160:163], v174 offset:33792
	ds_read_b128 v[180:183], v174 offset:34816
	ds_read_b128 v[184:187], v174 offset:35840
	ds_read_b128 v[188:191], v174 offset:36864
	ds_read_b128 v[192:195], v174 offset:37888
	ds_read_b128 v[222:225], v174 offset:38912
	global_load_lds_dwordx4 v0, s[98:99]
	s_mov_b32 m0, s69
	ds_read_b128 v[226:229], v174 offset:39936
	global_load_lds_dwordx4 v2, s[98:99]
	s_waitcnt lgkmcnt(8)
	s_barrier
	s_waitcnt lgkmcnt(0)
	v_mfma_f32_16x16x32_bf16 v[132:135], v[140:143], v[156:159], v[132:135]
	v_mfma_f32_16x16x32_bf16 v[128:131], v[148:151], v[156:159], v[128:131]
	v_mfma_f32_16x16x32_bf16 v[116:119], v[140:143], v[180:183], v[116:119]
	v_mfma_f32_16x16x32_bf16 v[112:115], v[148:151], v[180:183], v[112:115]
	v_mfma_f32_16x16x32_bf16 v[100:103], v[140:143], v[188:191], v[100:103]
	v_mfma_f32_16x16x32_bf16 v[96:99], v[148:151], v[188:191], v[96:99]
	v_mfma_f32_16x16x32_bf16 v[84:87], v[140:143], v[222:225], v[84:87]
	v_mfma_f32_16x16x32_bf16 v[80:83], v[148:151], v[222:225], v[80:83]
	v_mfma_f32_16x16x32_bf16 v[132:135], v[144:147], v[160:163], v[132:135]
	v_mfma_f32_16x16x32_bf16 v[128:131], v[152:155], v[160:163], v[128:131]
	v_mfma_f32_16x16x32_bf16 v[116:119], v[144:147], v[184:187], v[116:119]
	v_mfma_f32_16x16x32_bf16 v[112:115], v[152:155], v[184:187], v[112:115]
	v_mfma_f32_16x16x32_bf16 v[100:103], v[144:147], v[192:195], v[100:103]
	v_mfma_f32_16x16x32_bf16 v[96:99], v[152:155], v[192:195], v[96:99]
	v_mfma_f32_16x16x32_bf16 v[84:87], v[144:147], v[226:229], v[84:87]
	v_mfma_f32_16x16x32_bf16 v[80:83], v[152:155], v[226:229], v[80:83]
	s_barrier
	s_add_i32 m0, s65, 0x18000
	ds_read_b128 v[230:233], v217 offset:49152
	ds_read_b128 v[234:237], v217 offset:50176
	ds_read_b128 v[238:241], v217 offset:51200
	s_add_u32 s98, s60, 0x80
	s_addc_u32 s99, s61, 0
	global_load_lds_dwordx4 v0, s[98:99]
	s_add_i32 m0, s65, 0x1a000
	ds_read_b128 v[242:245], v217 offset:52224
	global_load_lds_dwordx4 v2, s[98:99]
	s_barrier
	s_waitcnt lgkmcnt(0)
	v_mfma_f32_16x16x32_bf16 v[124:127], v[230:233], v[156:159], v[124:127]
	v_mfma_f32_16x16x32_bf16 v[120:123], v[238:241], v[156:159], v[120:123]
	v_mfma_f32_16x16x32_bf16 v[108:111], v[230:233], v[180:183], v[108:111]
	v_mfma_f32_16x16x32_bf16 v[104:107], v[238:241], v[180:183], v[104:107]
	v_mfma_f32_16x16x32_bf16 v[92:95], v[230:233], v[188:191], v[92:95]
	v_mfma_f32_16x16x32_bf16 v[88:91], v[238:241], v[188:191], v[88:91]
	v_mfma_f32_16x16x32_bf16 v[76:79], v[230:233], v[222:225], v[76:79]
	v_mfma_f32_16x16x32_bf16 v[72:75], v[238:241], v[222:225], v[72:75]
	v_mfma_f32_16x16x32_bf16 v[124:127], v[234:237], v[160:163], v[124:127]
	v_mfma_f32_16x16x32_bf16 v[120:123], v[242:245], v[160:163], v[120:123]
	v_mfma_f32_16x16x32_bf16 v[108:111], v[234:237], v[184:187], v[108:111]
	v_mfma_f32_16x16x32_bf16 v[104:107], v[242:245], v[184:187], v[104:107]
	v_mfma_f32_16x16x32_bf16 v[92:95], v[234:237], v[192:195], v[92:95]
	v_mfma_f32_16x16x32_bf16 v[88:91], v[242:245], v[192:195], v[88:91]
	v_mfma_f32_16x16x32_bf16 v[76:79], v[234:237], v[226:229], v[76:79]
	v_mfma_f32_16x16x32_bf16 v[72:75], v[242:245], v[226:229], v[72:75]
	s_mov_b32 m0, s70
	s_barrier
	ds_read_b128 v[156:159], v174 offset:49152
	ds_read_b128 v[160:163], v174 offset:50176
	ds_read_b128 v[180:183], v174 offset:51200
	ds_read_b128 v[184:187], v174 offset:52224
	ds_read_b128 v[188:191], v174 offset:53248
	ds_read_b128 v[192:195], v174 offset:54272
	ds_read_b128 v[222:225], v174 offset:55296
	s_add_u32 s98, s62, 0x80
	s_addc_u32 s99, s63, 0
	global_load_lds_dwordx4 v0, s[98:99]
	s_mov_b32 m0, s71
	ds_read_b128 v[226:229], v174 offset:56320
	global_load_lds_dwordx4 v2, s[98:99]
	s_barrier
	s_waitcnt lgkmcnt(0)
	v_mfma_f32_16x16x32_bf16 v[68:71], v[140:143], v[156:159], v[68:71]
	v_mfma_f32_16x16x32_bf16 v[64:67], v[148:151], v[156:159], v[64:67]
	v_mfma_f32_16x16x32_bf16 v[52:55], v[140:143], v[180:183], v[52:55]
	v_mfma_f32_16x16x32_bf16 v[48:51], v[148:151], v[180:183], v[48:51]
	v_mfma_f32_16x16x32_bf16 v[36:39], v[140:143], v[188:191], v[36:39]
	v_mfma_f32_16x16x32_bf16 v[32:35], v[148:151], v[188:191], v[32:35]
	v_mfma_f32_16x16x32_bf16 v[20:23], v[140:143], v[222:225], v[20:23]
	v_mfma_f32_16x16x32_bf16 v[16:19], v[148:151], v[222:225], v[16:19]
	v_mfma_f32_16x16x32_bf16 v[68:71], v[144:147], v[160:163], v[68:71]
	v_mfma_f32_16x16x32_bf16 v[64:67], v[152:155], v[160:163], v[64:67]
	v_mfma_f32_16x16x32_bf16 v[52:55], v[144:147], v[184:187], v[52:55]
	v_mfma_f32_16x16x32_bf16 v[48:51], v[152:155], v[184:187], v[48:51]
	v_mfma_f32_16x16x32_bf16 v[36:39], v[144:147], v[192:195], v[36:39]
	v_mfma_f32_16x16x32_bf16 v[32:35], v[152:155], v[192:195], v[32:35]
	v_mfma_f32_16x16x32_bf16 v[20:23], v[144:147], v[226:229], v[20:23]
	v_mfma_f32_16x16x32_bf16 v[16:19], v[152:155], v[226:229], v[16:19]
	s_barrier
	s_add_i32 m0, s65, 0x1c000
	s_add_u32 s56, s60, 0x100080
	s_addc_u32 s57, s61, 0
	global_load_lds_dwordx4 v0, s[56:57]
	s_add_i32 m0, s65, 0x1e000
	s_add_i32 s79, s79, 2
	global_load_lds_dwordx4 v2, s[56:57]
	s_add_u32 s77, s77, 0x100
	s_addc_u32 s78, s78, 0
	s_mov_b64 s[56:57], s[58:59]
	s_cmp_gt_u32 s79, 61
	s_cbranch_scc1 .LrotX_744
	s_add_u32 s58, s56, 0x100
	s_addc_u32 s59, s57, 0
	s_cmp_lg_u32 s79, 60
	s_cselect_b32 s63, s59, s47
	s_cselect_b32 s62, s58, s46
	s_cselect_b32 s61, s78, s15
	s_cselect_b32 s60, s77, s49
; #define G_MMA(ai, bj, At, Bt) do { __builtin_amdgcn_s_setprio(1); _Pragma("unroll") for (int m = 0; m < 4; ++m) _Pragma("unroll") for (int n = 0; n < 2; ++n) _Pragma("unroll") for (int k = 0; k < 2; ++k) \
;         acc[ai][bj][m][n] = MFMA16(Bt[n][k], At[m][k], acc[ai][bj][m][n]); __builtin_amdgcn_s_setprio(0); } while (0)
; #define G_WAIT_V(n) asm volatile("s_waitcnt vmcnt(" #n ")" ::: "memory")
; #define G_BAR __builtin_amdgcn_s_barrier()
; template <class Epi>
; __device__ __forceinline__ void gemm_phase(LAS unsigned char* lds, const bf16_t* Ag, const bf16_t* Btg, const int K, const int nM, const int nN, const Epi& E) {
;     ...
;             G_WAIT_V(6); G_BAR; G_MMA(1, 1, At, B1); G_BAR;
;         }
.LrotX_744:
	s_waitcnt vmcnt(6)
	s_barrier
	v_mfma_f32_16x16x32_bf16 v[60:63], v[230:233], v[156:159], v[60:63]
	v_mfma_f32_16x16x32_bf16 v[56:59], v[238:241], v[156:159], v[56:59]
	v_mfma_f32_16x16x32_bf16 v[44:47], v[230:233], v[180:183], v[44:47]
	v_mfma_f32_16x16x32_bf16 v[40:43], v[238:241], v[180:183], v[40:43]
	v_mfma_f32_16x16x32_bf16 v[28:31], v[230:233], v[188:191], v[28:31]
	v_mfma_f32_16x16x32_bf16 v[24:27], v[238:241], v[188:191], v[24:27]
	v_mfma_f32_16x16x32_bf16 v[12:15], v[230:233], v[222:225], v[12:15]
	v_mfma_f32_16x16x32_bf16 v[8:11], v[238:241], v[222:225], v[8:11]
	v_mfma_f32_16x16x32_bf16 v[60:63], v[234:237], v[160:163], v[60:63]
	v_mfma_f32_16x16x32_bf16 v[56:59], v[242:245], v[160:163], v[56:59]
	v_mfma_f32_16x16x32_bf16 v[44:47], v[234:237], v[184:187], v[44:47]
	v_mfma_f32_16x16x32_bf16 v[40:43], v[242:245], v[184:187], v[40:43]
	v_mfma_f32_16x16x32_bf16 v[28:31], v[234:237], v[192:195], v[28:31]
	v_mfma_f32_16x16x32_bf16 v[24:27], v[242:245], v[192:195], v[24:27]
	v_mfma_f32_16x16x32_bf16 v[12:15], v[234:237], v[226:229], v[12:15]
	v_mfma_f32_16x16x32_bf16 v[8:11], v[242:245], v[226:229], v[8:11]
	s_cmp_lt_u32 s79, 60
	s_barrier
	s_cbranch_scc1 .LmainW_744
	s_cmp_gt_u32 s79, 61
	s_cbranch_scc1 .LBB0_748

; #define G_STAGE(bufoff, gbase) do { _Pragma("unroll") for (int _i = 0; _i < 2; ++_i) \
;         __builtin_amdgcn_global_load_lds((const unsigned*)((const char*)(gbase) + voff[_i]), (LAS unsigned*)(lds + (bufoff) + ldsw + _i * 8192), 16, 0, 0); } while (0)
; #define G_LDA(dst, b, h) do { _Pragma("unroll") for (int m = 0; m < 4; ++m) _Pragma("unroll") for (int k = 0; k < 2; ++k) dst[m][k] = *(const LAS bf16x8*)(lds + G_SA(b, h) + aoff + m * 2048 + k * 1024); } while (0)
; #define G_LDB(dst, b, h) do { _Pragma("unroll") for (int n = 0; n < 2; ++n) _Pragma("unroll") for (int k = 0; k < 2; ++k) dst[n][k] = *(const LAS bf16x8*)(lds + G_SB(b, h) + boff + n * 2048 + k * 1024); } while (0)
; #define G_MMA(ai, bj, At, Bt) do { __builtin_amdgcn_s_setprio(1); _Pragma("unroll") for (int m = 0; m < 4; ++m) _Pragma("unroll") for (int n = 0; n < 2; ++n) _Pragma("unroll") for (int k = 0; k < 2; ++k) \
;         acc[ai][bj][m][n] = MFMA16(Bt[n][k], At[m][k], acc[ai][bj][m][n]); __builtin_amdgcn_s_setprio(0); } while (0)
; #define G_WAIT_V(n) asm volatile("s_waitcnt vmcnt(" #n ")" ::: "memory")
; #define G_WAIT_L(n) asm volatile("s_waitcnt lgkmcnt(" #n ")" ::: "memory")
; #define G_BAR __builtin_amdgcn_s_barrier()
; #define G_SCHED __builtin_amdgcn_sched_barrier(0)
; template <class Epi>
; __device__ __forceinline__ void gemm_phase(LAS unsigned char* lds, const bf16_t* Ag, const bf16_t* Btg, const int K, const int nM, const int nN, const Epi& E) {
;     ...
;             G_LDB(B0, 0, 0); G_SCHED; G_LDA(At, 0, 0); G_STAGE(G_SA(1, 1), a1 + hstep);
;             G_WAIT_L(8); G_BAR; G_WAIT_L(0); G_MMA(0, 0, At, B0); G_BAR; G_SCHED;
;             G_LDB(B1, 0, 1); G_STAGE(G_SB(0, 0), b2);
;             G_BAR; G_WAIT_L(0); G_MMA(0, 1, At, B1); G_BAR;
;             G_LDA(At, 0, 1); G_STAGE(G_SA(0, 0), a2);
;             G_BAR; G_WAIT_L(0); G_MMA(1, 0, At, B0); G_BAR; G_SCHED;
;             G_STAGE(G_SB(0, 1), b2 + hstep);
;             G_WAIT_V(6); G_BAR; G_MMA(1, 1, At, B1); G_BAR;
.LmainW_848:
	ds_read_b128 v[130:133], v217
	ds_read_b128 v[134:137], v217 offset:1024
	ds_read_b128 v[144:147], v217 offset:2048
	ds_read_b128 v[148:151], v217 offset:3072
	s_add_i32 m0, s60, 0xc000
	ds_read_b128 v[156:159], v222
	ds_read_b128 v[160:163], v222 offset:1024
	ds_read_b128 v[164:167], v222 offset:2048
	ds_read_b128 v[180:183], v222 offset:3072
	ds_read_b128 v[184:187], v222 offset:4096
	ds_read_b128 v[224:227], v222 offset:5120
	ds_read_b128 v[228:231], v222 offset:6144
	global_load_lds_dwordx4 v170, s[50:51]
	s_add_i32 m0, s60, 0xe000
	ds_read_b128 v[232:235], v222 offset:7168
	global_load_lds_dwordx4 v168, s[50:51]
	s_waitcnt lgkmcnt(8)
	s_barrier
	s_waitcnt lgkmcnt(0)
	v_mfma_f32_16x16x32_bf16 v[152:155], v[130:133], v[156:159], v[152:155]
	v_mfma_f32_16x16x32_bf16 v[138:141], v[144:147], v[156:159], v[140:143]
	v_mfma_f32_16x16x32_bf16 v[116:119], v[130:133], v[164:167], v[116:119]
	v_mfma_f32_16x16x32_bf16 v[112:115], v[144:147], v[164:167], v[112:115]
	v_mfma_f32_16x16x32_bf16 v[100:103], v[130:133], v[184:187], v[100:103]
	v_mfma_f32_16x16x32_bf16 v[96:99], v[144:147], v[184:187], v[96:99]
	v_mfma_f32_16x16x32_bf16 v[84:87], v[130:133], v[228:231], v[84:87]
	v_mfma_f32_16x16x32_bf16 v[80:83], v[144:147], v[228:231], v[80:83]
	v_mfma_f32_16x16x32_bf16 v[152:155], v[134:137], v[160:163], v[152:155]
	v_mfma_f32_16x16x32_bf16 v[138:141], v[148:151], v[160:163], v[138:141]
	v_mfma_f32_16x16x32_bf16 v[116:119], v[134:137], v[180:183], v[116:119]
	v_mfma_f32_16x16x32_bf16 v[112:115], v[148:151], v[180:183], v[112:115]
	v_mfma_f32_16x16x32_bf16 v[100:103], v[134:137], v[224:227], v[100:103]
	v_mfma_f32_16x16x32_bf16 v[96:99], v[148:151], v[224:227], v[96:99]
	v_mfma_f32_16x16x32_bf16 v[84:87], v[134:137], v[232:235], v[84:87]
	v_mfma_f32_16x16x32_bf16 v[80:83], v[148:151], v[232:235], v[80:83]
	s_barrier
	s_add_i32 s73, 0, 0x14000
	s_add_i32 m0, s59, 0x10000
	ds_read_b128 v[236:239], v217 offset:16384
	ds_read_b128 v[240:243], v217 offset:17408
	ds_read_b128 v[244:247], v217 offset:18432
	global_load_lds_dwordx4 v0, s[52:53]
	s_add_i32 m0, s59, 0x12000
	ds_read_b128 v[248:251], v217 offset:19456
	global_load_lds_dwordx4 v2, s[52:53]
	s_barrier
	s_waitcnt lgkmcnt(0)
	v_mfma_f32_16x16x32_bf16 v[124:127], v[236:239], v[156:159], v[124:127]
	v_mfma_f32_16x16x32_bf16 v[120:123], v[244:247], v[156:159], v[120:123]
	v_mfma_f32_16x16x32_bf16 v[108:111], v[236:239], v[164:167], v[108:111]
	v_mfma_f32_16x16x32_bf16 v[104:107], v[244:247], v[164:167], v[104:107]
	v_mfma_f32_16x16x32_bf16 v[92:95], v[236:239], v[184:187], v[92:95]
	v_mfma_f32_16x16x32_bf16 v[88:91], v[244:247], v[184:187], v[88:91]
	v_mfma_f32_16x16x32_bf16 v[76:79], v[236:239], v[228:231], v[76:79]
	v_mfma_f32_16x16x32_bf16 v[72:75], v[244:247], v[228:231], v[72:75]
	v_mfma_f32_16x16x32_bf16 v[124:127], v[240:243], v[160:163], v[124:127]
	v_mfma_f32_16x16x32_bf16 v[120:123], v[248:251], v[160:163], v[120:123]
	v_mfma_f32_16x16x32_bf16 v[108:111], v[240:243], v[180:183], v[108:111]
	v_mfma_f32_16x16x32_bf16 v[104:107], v[248:251], v[180:183], v[104:107]
	v_mfma_f32_16x16x32_bf16 v[92:95], v[240:243], v[224:227], v[92:95]
	v_mfma_f32_16x16x32_bf16 v[88:91], v[248:251], v[224:227], v[88:91]
	v_mfma_f32_16x16x32_bf16 v[76:79], v[240:243], v[232:235], v[76:79]
	v_mfma_f32_16x16x32_bf16 v[72:75], v[248:251], v[232:235], v[72:75]
	s_mov_b32 m0, s60
	s_add_u32 s76, s54, 0x80
	s_addc_u32 s77, s55, 0
	s_barrier
	ds_read_b128 v[156:159], v222 offset:16384
	ds_read_b128 v[160:163], v222 offset:17408
	ds_read_b128 v[164:167], v222 offset:18432
	ds_read_b128 v[180:183], v222 offset:19456
	ds_read_b128 v[184:187], v222 offset:20480
	ds_read_b128 v[224:227], v222 offset:21504
	ds_read_b128 v[228:231], v222 offset:22528
	ds_read_b128 v[232:235], v222 offset:23552
	global_load_lds_dwordx4 v0, s[54:55]
	s_add_u32 s76, s54, 0x80
	s_mov_b32 m0, s61
	s_addc_u32 s77, s55, 0
	global_load_lds_dwordx4 v2, s[54:55]
	s_barrier
	s_waitcnt lgkmcnt(0)
	v_mfma_f32_16x16x32_bf16 v[60:63], v[130:133], v[156:159], v[60:63]
	v_mfma_f32_16x16x32_bf16 v[56:59], v[144:147], v[156:159], v[56:59]
	v_mfma_f32_16x16x32_bf16 v[44:47], v[130:133], v[164:167], v[44:47]
	v_mfma_f32_16x16x32_bf16 v[40:43], v[144:147], v[164:167], v[40:43]
	v_mfma_f32_16x16x32_bf16 v[28:31], v[130:133], v[184:187], v[28:31]
	v_mfma_f32_16x16x32_bf16 v[24:27], v[144:147], v[184:187], v[24:27]
	v_mfma_f32_16x16x32_bf16 v[12:15], v[130:133], v[228:231], v[12:15]
	v_mfma_f32_16x16x32_bf16 v[8:11], v[144:147], v[228:231], v[8:11]
	v_mfma_f32_16x16x32_bf16 v[60:63], v[134:137], v[160:163], v[60:63]
	v_mfma_f32_16x16x32_bf16 v[56:59], v[148:151], v[160:163], v[56:59]
	v_mfma_f32_16x16x32_bf16 v[44:47], v[134:137], v[180:183], v[44:47]
	v_mfma_f32_16x16x32_bf16 v[40:43], v[148:151], v[180:183], v[40:43]
	v_mfma_f32_16x16x32_bf16 v[28:31], v[134:137], v[224:227], v[28:31]
	v_mfma_f32_16x16x32_bf16 v[24:27], v[148:151], v[224:227], v[24:27]
	v_mfma_f32_16x16x32_bf16 v[12:15], v[134:137], v[232:235], v[12:15]
	v_mfma_f32_16x16x32_bf16 v[8:11], v[148:151], v[232:235], v[8:11]
	s_barrier
	s_add_i32 m0, s59, 0x14000
	s_add_u32 s74, s52, 0x40000
	s_addc_u32 s75, s53, 0
	global_load_lds_dwordx4 v0, s[74:75]
	s_add_i32 m0, s59, 0x16000
	s_add_u32 s54, s54, 0x40000
	s_addc_u32 s55, s55, 0
	global_load_lds_dwordx4 v2, s[74:75]
	s_waitcnt vmcnt(6)
	s_barrier
;     __device__ __forceinline__ void prep(int pm, int par, LAS unsigned char* lds) const { if (fold) prep_rowstats(stat, pm, par, lds); }
;     __device__ __forceinline__ void prep(int pm, int par, LAS unsigned char* lds) const { if (!ident) prep_rowstats(stat, pm, par, lds); }
;     __device__ __forceinline__ void prep(int pm, int par, LAS unsigned char* lds) const { prep_rowstats(stat, pm, par, lds); }
; #define G_STAGE(bufoff, gbase) do { _Pragma("unroll") for (int _i = 0; _i < 2; ++_i) \
;         __builtin_amdgcn_global_load_lds((const unsigned*)((const char*)(gbase) + voff[_i]), (LAS unsigned*)(lds + (bufoff) + ldsw + _i * 8192), 16, 0, 0); } while (0)
; #define G_WAIT_V(n) asm volatile("s_waitcnt vmcnt(" #n ")" ::: "memory")
; #define G_BAR __builtin_amdgcn_s_barrier()
; template <class Epi>
; __device__ __forceinline__ void gemm_phase(LAS unsigned char* lds, const bf16_t* Ag, const bf16_t* Btg, const int K, const int nM, const int nN, const Epi& E) {
;     ...
;         for (int t = 0; t < nt; t += 2) {
;             const bool last = (t == nt - 2);
;             const char* a1 = cA + (size_t)(t + 1) * kstep;
;             const char* a2 = last ? nA : cA + (size_t)(t + 2) * kstep; const char* b2 = last ? nB : cB + (size_t)(t + 2) * kstep;
;             const char* a3 = a2 + kstep; const char* b3 = b2 + kstep;
;             if (last && has_next && pmn != pm) E.prep(pmn, par ^ 1, lds);
;             G_LDB(B0, 0, 0); G_SCHED; G_LDA(At, 0, 0); G_STAGE(G_SA(1, 1), a1 + hstep);
;             G_WAIT_L(8); G_BAR; G_WAIT_L(0); G_MMA(0, 0, At, B0); G_BAR; G_SCHED;
;             G_LDB(B1, 0, 1); G_STAGE(G_SB(0, 0), b2);
;             G_BAR; G_WAIT_L(0); G_MMA(0, 1, At, B1); G_BAR;
;             G_LDA(At, 0, 1); G_STAGE(G_SA(0, 0), a2);
;             G_BAR; G_WAIT_L(0); G_MMA(1, 0, At, B0); G_BAR; G_SCHED;
;             G_STAGE(G_SB(0, 1), b2 + hstep);
;             G_WAIT_V(6); G_BAR; G_MMA(1, 1, At, B1); G_BAR;
;             G_LDB(B0, 1, 0); G_SCHED; G_LDA(At, 1, 0); G_STAGE(G_SA(0, 1), a2 + hstep);
;             G_WAIT_L(8); G_BAR; G_WAIT_L(0); G_MMA(0, 0, At, B0); G_BAR; G_SCHED;
;             G_LDB(B1, 1, 1); G_STAGE(G_SB(1, 0), b3);
;             G_BAR; G_WAIT_L(0); G_MMA(0, 1, At, B1); G_BAR;
;             G_LDA(At, 1, 1); G_STAGE(G_SA(1, 0), a3);
;             G_BAR; G_WAIT_L(0); G_MMA(1, 0, At, B0); G_BAR; G_SCHED;
;             G_STAGE(G_SB(1, 1), b3 + hstep);
	v_mfma_f32_16x16x32_bf16 v[68:71], v[236:239], v[156:159], v[68:71]
	v_mfma_f32_16x16x32_bf16 v[64:67], v[244:247], v[156:159], v[64:67]
	v_mfma_f32_16x16x32_bf16 v[52:55], v[236:239], v[164:167], v[52:55]
	v_mfma_f32_16x16x32_bf16 v[48:51], v[244:247], v[164:167], v[48:51]
	v_mfma_f32_16x16x32_bf16 v[36:39], v[236:239], v[184:187], v[36:39]
	v_mfma_f32_16x16x32_bf16 v[32:35], v[244:247], v[184:187], v[32:35]
	v_mfma_f32_16x16x32_bf16 v[20:23], v[236:239], v[228:231], v[20:23]
	v_mfma_f32_16x16x32_bf16 v[16:19], v[244:247], v[228:231], v[16:19]
	v_mfma_f32_16x16x32_bf16 v[68:71], v[240:243], v[160:163], v[68:71]
	v_mfma_f32_16x16x32_bf16 v[64:67], v[248:251], v[160:163], v[64:67]
	v_mfma_f32_16x16x32_bf16 v[52:55], v[240:243], v[180:183], v[52:55]
	v_mfma_f32_16x16x32_bf16 v[48:51], v[248:251], v[180:183], v[48:51]
	v_mfma_f32_16x16x32_bf16 v[36:39], v[240:243], v[224:227], v[36:39]
	v_mfma_f32_16x16x32_bf16 v[32:35], v[248:251], v[224:227], v[32:35]
	v_mfma_f32_16x16x32_bf16 v[20:23], v[240:243], v[232:235], v[20:23]
	v_mfma_f32_16x16x32_bf16 v[16:19], v[248:251], v[232:235], v[16:19]
	s_barrier
	ds_read_b128 v[130:133], v217 offset:32768
	ds_read_b128 v[134:137], v217 offset:33792
	ds_read_b128 v[144:147], v217 offset:34816
	ds_read_b128 v[148:151], v217 offset:35840
	s_mov_b32 m0, s62
	ds_read_b128 v[156:159], v222 offset:32768
	ds_read_b128 v[160:163], v222 offset:33792
	ds_read_b128 v[164:167], v222 offset:34816
	ds_read_b128 v[180:183], v222 offset:35840
	ds_read_b128 v[184:187], v222 offset:36864
	ds_read_b128 v[224:227], v222 offset:37888
	ds_read_b128 v[228:231], v222 offset:38912
	global_load_lds_dwordx4 v0, s[54:55]
	s_mov_b32 m0, s63
	ds_read_b128 v[232:235], v222 offset:39936
	global_load_lds_dwordx4 v2, s[54:55]
	s_waitcnt lgkmcnt(8)
	s_barrier
	s_waitcnt lgkmcnt(0)
	v_mfma_f32_16x16x32_bf16 v[152:155], v[130:133], v[156:159], v[152:155]
	v_mfma_f32_16x16x32_bf16 v[138:141], v[144:147], v[156:159], v[138:141]
	v_mfma_f32_16x16x32_bf16 v[116:119], v[130:133], v[164:167], v[116:119]
	v_mfma_f32_16x16x32_bf16 v[112:115], v[144:147], v[164:167], v[112:115]
	v_mfma_f32_16x16x32_bf16 v[100:103], v[130:133], v[184:187], v[100:103]
	v_mfma_f32_16x16x32_bf16 v[96:99], v[144:147], v[184:187], v[96:99]
	v_mfma_f32_16x16x32_bf16 v[84:87], v[130:133], v[228:231], v[84:87]
	v_mfma_f32_16x16x32_bf16 v[80:83], v[144:147], v[228:231], v[80:83]
	v_mfma_f32_16x16x32_bf16 v[152:155], v[134:137], v[160:163], v[152:155]
	v_mfma_f32_16x16x32_bf16 v[140:143], v[148:151], v[160:163], v[138:141]
	v_mfma_f32_16x16x32_bf16 v[116:119], v[134:137], v[180:183], v[116:119]
	v_mfma_f32_16x16x32_bf16 v[112:115], v[148:151], v[180:183], v[112:115]
	v_mfma_f32_16x16x32_bf16 v[100:103], v[134:137], v[224:227], v[100:103]
	v_mfma_f32_16x16x32_bf16 v[96:99], v[148:151], v[224:227], v[96:99]
	v_mfma_f32_16x16x32_bf16 v[84:87], v[134:137], v[232:235], v[84:87]
	v_mfma_f32_16x16x32_bf16 v[80:83], v[148:151], v[232:235], v[80:83]
	s_barrier
	s_add_i32 m0, s59, 0x18000
	ds_read_b128 v[236:239], v217 offset:49152
	ds_read_b128 v[240:243], v217 offset:50176
	ds_read_b128 v[244:247], v217 offset:51200
	s_add_u32 s98, s52, 0x80
	s_addc_u32 s99, s53, 0
	global_load_lds_dwordx4 v0, s[98:99]
	s_add_i32 m0, s59, 0x1a000
	ds_read_b128 v[248:251], v217 offset:52224
	global_load_lds_dwordx4 v2, s[98:99]
	s_barrier
	s_waitcnt lgkmcnt(0)
	v_mfma_f32_16x16x32_bf16 v[124:127], v[236:239], v[156:159], v[124:127]
	v_mfma_f32_16x16x32_bf16 v[120:123], v[244:247], v[156:159], v[120:123]
	v_mfma_f32_16x16x32_bf16 v[108:111], v[236:239], v[164:167], v[108:111]
	v_mfma_f32_16x16x32_bf16 v[104:107], v[244:247], v[164:167], v[104:107]
	v_mfma_f32_16x16x32_bf16 v[92:95], v[236:239], v[184:187], v[92:95]
	v_mfma_f32_16x16x32_bf16 v[88:91], v[244:247], v[184:187], v[88:91]
	v_mfma_f32_16x16x32_bf16 v[76:79], v[236:239], v[228:231], v[76:79]
	v_mfma_f32_16x16x32_bf16 v[72:75], v[244:247], v[228:231], v[72:75]
	v_mfma_f32_16x16x32_bf16 v[124:127], v[240:243], v[160:163], v[124:127]
	v_mfma_f32_16x16x32_bf16 v[120:123], v[248:251], v[160:163], v[120:123]
	v_mfma_f32_16x16x32_bf16 v[108:111], v[240:243], v[180:183], v[108:111]
	v_mfma_f32_16x16x32_bf16 v[104:107], v[248:251], v[180:183], v[104:107]
	v_mfma_f32_16x16x32_bf16 v[92:95], v[240:243], v[224:227], v[92:95]
	v_mfma_f32_16x16x32_bf16 v[88:91], v[248:251], v[224:227], v[88:91]
	v_mfma_f32_16x16x32_bf16 v[76:79], v[240:243], v[232:235], v[76:79]
	v_mfma_f32_16x16x32_bf16 v[72:75], v[248:251], v[232:235], v[72:75]
	s_mov_b32 m0, s64
	s_barrier
	ds_read_b128 v[156:159], v222 offset:49152
	ds_read_b128 v[160:163], v222 offset:50176
	ds_read_b128 v[164:167], v222 offset:51200
	ds_read_b128 v[180:183], v222 offset:52224
	ds_read_b128 v[184:187], v222 offset:53248
	ds_read_b128 v[224:227], v222 offset:54272
	ds_read_b128 v[228:231], v222 offset:55296
	global_load_lds_dwordx4 v0, s[76:77]
	s_mov_b32 m0, s65
	ds_read_b128 v[232:235], v222 offset:56320
	global_load_lds_dwordx4 v2, s[76:77]
	s_barrier
	s_waitcnt lgkmcnt(0)
	v_mfma_f32_16x16x32_bf16 v[60:63], v[130:133], v[156:159], v[60:63]
	v_mfma_f32_16x16x32_bf16 v[56:59], v[144:147], v[156:159], v[56:59]
	v_mfma_f32_16x16x32_bf16 v[44:47], v[130:133], v[164:167], v[44:47]
	v_mfma_f32_16x16x32_bf16 v[40:43], v[144:147], v[164:167], v[40:43]
	v_mfma_f32_16x16x32_bf16 v[28:31], v[130:133], v[184:187], v[28:31]
	v_mfma_f32_16x16x32_bf16 v[24:27], v[144:147], v[184:187], v[24:27]
	v_mfma_f32_16x16x32_bf16 v[12:15], v[130:133], v[228:231], v[12:15]
	v_mfma_f32_16x16x32_bf16 v[8:11], v[144:147], v[228:231], v[8:11]
	v_mfma_f32_16x16x32_bf16 v[60:63], v[134:137], v[160:163], v[60:63]
	v_mfma_f32_16x16x32_bf16 v[56:59], v[148:151], v[160:163], v[56:59]
	v_mfma_f32_16x16x32_bf16 v[44:47], v[134:137], v[180:183], v[44:47]
	v_mfma_f32_16x16x32_bf16 v[40:43], v[148:151], v[180:183], v[40:43]
	v_mfma_f32_16x16x32_bf16 v[28:31], v[134:137], v[224:227], v[28:31]
	v_mfma_f32_16x16x32_bf16 v[24:27], v[148:151], v[224:227], v[24:27]
	v_mfma_f32_16x16x32_bf16 v[12:15], v[134:137], v[232:235], v[12:15]
	v_mfma_f32_16x16x32_bf16 v[8:11], v[148:151], v[232:235], v[8:11]
	s_barrier
	s_add_i32 m0, s59, 0x1c000
	s_add_u32 s52, s52, 0x40080
	s_addc_u32 s53, s53, 0
	global_load_lds_dwordx4 v0, s[52:53]
	s_add_i32 m0, s59, 0x1e000
	s_add_i32 s72, s72, 2
	global_load_lds_dwordx4 v2, s[52:53]
	s_add_u32 s70, s70, 0x100
	s_addc_u32 s71, s71, 0
	s_add_u32 s50, s50, 0x100
	s_addc_u32 s51, s51, 0
	s_cmp_gt_u32 s72, 13
	s_cbranch_scc1 .LrotX_848
	s_add_u32 s26, s50, 0xfffc0080
	s_addc_u32 s54, s51, -1
	s_cmp_lg_u32 s72, 12
	s_cselect_b32 s55, s54, s25
	s_cselect_b32 s54, s26, s24
	s_cselect_b32 s53, s71, s14
	s_cselect_b32 s52, s70, s15
; #define G_MMA(ai, bj, At, Bt) do { __builtin_amdgcn_s_setprio(1); _Pragma("unroll") for (int m = 0; m < 4; ++m) _Pragma("unroll") for (int n = 0; n < 2; ++n) _Pragma("unroll") for (int k = 0; k < 2; ++k) \
;         acc[ai][bj][m][n] = MFMA16(Bt[n][k], At[m][k], acc[ai][bj][m][n]); __builtin_amdgcn_s_setprio(0); } while (0)
; #define G_WAIT_V(n) asm volatile("s_waitcnt vmcnt(" #n ")" ::: "memory")
; #define G_BAR __builtin_amdgcn_s_barrier()
; template <class Epi>
; __device__ __forceinline__ void gemm_phase(LAS unsigned char* lds, const bf16_t* Ag, const bf16_t* Btg, const int K, const int nM, const int nN, const Epi& E) {
;     ...
;             G_WAIT_V(6); G_BAR; G_MMA(1, 1, At, B1); G_BAR;
;         }
.LrotX_848:
	s_waitcnt vmcnt(6)
	s_barrier
	v_mfma_f32_16x16x32_bf16 v[68:71], v[236:239], v[156:159], v[68:71]
	v_mfma_f32_16x16x32_bf16 v[64:67], v[244:247], v[156:159], v[64:67]
	v_mfma_f32_16x16x32_bf16 v[52:55], v[236:239], v[164:167], v[52:55]
	v_mfma_f32_16x16x32_bf16 v[48:51], v[244:247], v[164:167], v[48:51]
	v_mfma_f32_16x16x32_bf16 v[36:39], v[236:239], v[184:187], v[36:39]
	v_mfma_f32_16x16x32_bf16 v[32:35], v[244:247], v[184:187], v[32:35]
	v_mfma_f32_16x16x32_bf16 v[20:23], v[236:239], v[228:231], v[20:23]
	v_mfma_f32_16x16x32_bf16 v[16:19], v[244:247], v[228:231], v[16:19]
	v_mfma_f32_16x16x32_bf16 v[68:71], v[240:243], v[160:163], v[68:71]
	v_mfma_f32_16x16x32_bf16 v[64:67], v[248:251], v[160:163], v[64:67]
	v_mfma_f32_16x16x32_bf16 v[52:55], v[240:243], v[180:183], v[52:55]
	v_mfma_f32_16x16x32_bf16 v[48:51], v[248:251], v[180:183], v[48:51]
	v_mfma_f32_16x16x32_bf16 v[36:39], v[240:243], v[224:227], v[36:39]
	v_mfma_f32_16x16x32_bf16 v[32:35], v[248:251], v[224:227], v[32:35]
	v_mfma_f32_16x16x32_bf16 v[20:23], v[240:243], v[232:235], v[20:23]
	v_mfma_f32_16x16x32_bf16 v[16:19], v[248:251], v[232:235], v[16:19]
	s_cmp_lt_u32 s72, 12
	s_barrier
	s_cbranch_scc1 .LmainW_848
	s_cmp_gt_u32 s72, 13
	s_cbranch_scc1 .LBB0_852
